# plus batched out-proj residual epilogue, single-fetch rope in prep_mla q epilogue, batched weight-tile loads, DN doubling-step LDS reads issued upfront
# speedup vs baseline: 1.0256x; 1.0256x over previous
; DI void wtrans_tile(const float* __restrict__ src, int K, int N, u16* __restrict__ dst, int ldw, int tk, int tn,
;                     const float* __restrict__ kscale, char* lds) {
;     ...
;   const int tid = tid_, j = tid & 63, i0 = tid >> 6;
;   const int k0 = tk * 64, n0 = tn * 64;
;   __syncthreads();
; #pragma unroll
;   for (int q = 0; q < 16; ++q) {
;     int i = i0 + 4 * q;
;     float v = (n0 + j < N) ? src[(size_t)(k0 + i) * N + n0 + j] : 0.f;
;     if (kscale) v *= kscale[k0 + i];
;     t[i * 65 + j] = v;
;   }
.LBB0_119:
	s_andn2_b64 vcc, exec, s[8:9]
	s_cbranch_vccnz .LBB0_122
	s_lshl_b32 s8, s12, 2
	s_and_b32 s8, s8, 0x3fc0
	v_mov_b32_e32 v0, v248
	s_add_i32 s26, s8, 0xffffe100
	s_lshl_b32 s8, s12, 6
	s_and_b32 s8, s8, 0x3c0
	v_readlane_b32 s76, v250, 16
	v_and_b32_e32 v1, 63, v0
	v_ashrrev_i32_e32 v0, 6, v0
	s_lshl_b32 s9, s8, 2
	v_readlane_b32 s88, v250, 28
	v_readlane_b32 s89, v250, 29
	s_add_u32 s14, s88, s9
	v_add_u32_e32 v4, s26, v0
	s_addc_u32 s15, s89, 0
	v_lshlrev_b32_e32 v74, 2, v1
	v_ashrrev_i32_e32 v5, 31, v4
	v_lshl_add_u64 v[2:3], s[14:15], 0, v[74:75]
	v_lshlrev_b64 v[6:7], 12, v[4:5]
	v_lshl_add_u64 v[6:7], v[2:3], 0, v[6:7]
	s_waitcnt lgkmcnt(0)
	s_barrier
	global_load_dword v218, v[6:7], off
	v_readlane_b32 s88, v250, 35
	v_mul_lo_u32 v6, v0, s57
	s_lshl_b64 s[14:15], s[26:27], 1
	v_add3_u32 v8, s88, v6, v74
	v_add_u32_e32 v6, 4, v4
	v_ashrrev_i32_e32 v7, 31, v6
	v_lshlrev_b64 v[6:7], 12, v[6:7]
	v_lshl_add_u64 v[6:7], v[2:3], 0, v[6:7]
	v_readlane_b32 s84, v250, 24
	v_readlane_b32 s85, v250, 25
	s_add_u32 s14, s65, s14
	v_readlane_b32 s84, v250, 33
	s_addc_u32 s15, s66, s15
	v_lshlrev_b32_e32 v74, 1, v1
	v_readlane_b32 s85, v250, 34
	s_mov_b32 s9, 16
	s_mov_b32 s13, 1
	v_readlane_b32 s77, v250, 17
	v_readlane_b32 s78, v250, 18
	v_readlane_b32 s79, v250, 19
	v_readlane_b32 s80, v250, 20
	v_readlane_b32 s81, v250, 21
	v_readlane_b32 s82, v250, 22
	v_readlane_b32 s83, v250, 23
	v_readlane_b32 s86, v250, 26
	v_readlane_b32 s87, v250, 27
	v_readlane_b32 s90, v250, 30
	v_readlane_b32 s91, v250, 31
	global_load_dword v219, v[6:7], off
	v_add_u32_e32 v6, 8, v4
	v_ashrrev_i32_e32 v7, 31, v6
	v_lshlrev_b64 v[6:7], 12, v[6:7]
	v_lshl_add_u64 v[6:7], v[2:3], 0, v[6:7]
	global_load_dword v220, v[6:7], off
	v_add_u32_e32 v6, 12, v4
	v_ashrrev_i32_e32 v7, 31, v6
	v_lshlrev_b64 v[6:7], 12, v[6:7]
	v_lshl_add_u64 v[6:7], v[2:3], 0, v[6:7]
	global_load_dword v221, v[6:7], off
	v_add_u32_e32 v6, 16, v4
	v_ashrrev_i32_e32 v7, 31, v6
	v_lshlrev_b64 v[6:7], 12, v[6:7]
	v_lshl_add_u64 v[6:7], v[2:3], 0, v[6:7]
	global_load_dword v222, v[6:7], off
	v_add_u32_e32 v6, 20, v4
	v_ashrrev_i32_e32 v7, 31, v6
	v_lshlrev_b64 v[6:7], 12, v[6:7]
	v_lshl_add_u64 v[6:7], v[2:3], 0, v[6:7]
	global_load_dword v223, v[6:7], off
	v_add_u32_e32 v6, 24, v4
	v_ashrrev_i32_e32 v7, 31, v6
	v_lshlrev_b64 v[6:7], 12, v[6:7]
	v_lshl_add_u64 v[6:7], v[2:3], 0, v[6:7]
	global_load_dword v224, v[6:7], off
	v_add_u32_e32 v6, 28, v4
	v_ashrrev_i32_e32 v7, 31, v6
	v_lshlrev_b64 v[6:7], 12, v[6:7]
	v_lshl_add_u64 v[6:7], v[2:3], 0, v[6:7]
	global_load_dword v225, v[6:7], off
	v_add_u32_e32 v6, 32, v4
	v_ashrrev_i32_e32 v7, 31, v6
	v_lshlrev_b64 v[6:7], 12, v[6:7]
	v_lshl_add_u64 v[6:7], v[2:3], 0, v[6:7]
	global_load_dword v226, v[6:7], off
	v_add_u32_e32 v6, 36, v4
	v_ashrrev_i32_e32 v7, 31, v6
	v_lshlrev_b64 v[6:7], 12, v[6:7]
	v_lshl_add_u64 v[6:7], v[2:3], 0, v[6:7]
	global_load_dword v227, v[6:7], off
	v_add_u32_e32 v6, 40, v4
	v_ashrrev_i32_e32 v7, 31, v6
	v_lshlrev_b64 v[6:7], 12, v[6:7]
	v_lshl_add_u64 v[6:7], v[2:3], 0, v[6:7]
	global_load_dword v228, v[6:7], off
	v_add_u32_e32 v6, 44, v4
	v_ashrrev_i32_e32 v7, 31, v6
	v_lshlrev_b64 v[6:7], 12, v[6:7]
	v_lshl_add_u64 v[6:7], v[2:3], 0, v[6:7]
	global_load_dword v229, v[6:7], off
	v_add_u32_e32 v6, 48, v4
	v_ashrrev_i32_e32 v7, 31, v6
	v_lshlrev_b64 v[6:7], 12, v[6:7]
	v_lshl_add_u64 v[6:7], v[2:3], 0, v[6:7]
	global_load_dword v230, v[6:7], off
	v_add_u32_e32 v6, 52, v4
	v_ashrrev_i32_e32 v7, 31, v6
	v_lshlrev_b64 v[6:7], 12, v[6:7]
	v_lshl_add_u64 v[6:7], v[2:3], 0, v[6:7]
	global_load_dword v231, v[6:7], off
	v_add_u32_e32 v6, 56, v4
	v_ashrrev_i32_e32 v7, 31, v6
	v_lshlrev_b64 v[6:7], 12, v[6:7]
	v_lshl_add_u64 v[6:7], v[2:3], 0, v[6:7]
	v_add_u32_e32 v4, 60, v4
	global_load_dword v232, v[6:7], off
	v_add_u32_e32 v6, 16, v0
	v_mov_b32_e32 v7, v6
	v_ashrrev_i32_e32 v5, 31, v4
	v_lshlrev_b64 v[4:5], 12, v[4:5]
	v_lshl_add_u64 v[2:3], v[2:3], 0, v[4:5]
	global_load_dword v233, v[2:3], off
	v_mov_b32_e32 v4, s88
	v_mad_u32_u24 v10, v1, s57, v4
	v_add_u32_e32 v4, 8, v0
	v_mov_b32_e32 v1, v0
	v_mov_b32_e32 v5, v4
	s_waitcnt vmcnt(15)
	ds_write_b32 v8, v218
	s_waitcnt vmcnt(14)
	ds_write_b32 v8, v219 offset:1040
	s_waitcnt vmcnt(13)
	ds_write_b32 v8, v220 offset:2080
	s_waitcnt vmcnt(12)
	ds_write_b32 v8, v221 offset:3120
	s_waitcnt vmcnt(11)
	ds_write_b32 v8, v222 offset:4160
	s_waitcnt vmcnt(10)
	ds_write_b32 v8, v223 offset:5200
	s_waitcnt vmcnt(9)
	ds_write_b32 v8, v224 offset:6240
	s_waitcnt vmcnt(8)
	ds_write_b32 v8, v225 offset:7280
	s_waitcnt vmcnt(7)
	ds_write_b32 v8, v226 offset:8320
	s_waitcnt vmcnt(6)
	ds_write_b32 v8, v227 offset:9360
	s_waitcnt vmcnt(5)
	ds_write_b32 v8, v228 offset:10400
	s_waitcnt vmcnt(4)
	ds_write_b32 v8, v229 offset:11440
	s_waitcnt vmcnt(3)
	ds_write_b32 v8, v230 offset:12480
	s_waitcnt vmcnt(2)
	ds_write_b32 v8, v231 offset:13520
	s_waitcnt vmcnt(1)
	ds_write_b32 v8, v232 offset:14560
	s_waitcnt vmcnt(0)
	ds_write_b32 v8, v233 offset:15600
	v_add_u32_e32 v8, 24, v0
	v_lshl_add_u64 v[2:3], s[14:15], 0, v[74:75]
	s_mov_b32 s14, s8
	v_mov_b32_e32 v9, v8
	s_mov_b32 s15, 0
	s_waitcnt lgkmcnt(0)
	s_barrier

; DI void wtrans_tile(const float* __restrict__ src, int K, int N, u16* __restrict__ dst, int ldw, int tk, int tn,
;                     const float* __restrict__ kscale, char* lds) {
;     ...
;   const int tid = tid_, j = tid & 63, i0 = tid >> 6;
;   const int k0 = tk * 64, n0 = tn * 64;
;   __syncthreads();
; #pragma unroll
;   for (int q = 0; q < 16; ++q) {
;     int i = i0 + 4 * q;
;     float v = (n0 + j < N) ? src[(size_t)(k0 + i) * N + n0 + j] : 0.f;
;     if (kscale) v *= kscale[k0 + i];
;     t[i * 65 + j] = v;
;   }
.LBB0_123:
	s_andn2_b64 vcc, exec, s[8:9]
	s_cbranch_vccnz .LBB0_126
	s_and_b32 s8, s12, 0x7c0
	s_add_i32 s26, s8, 0xfffffc40
	v_mov_b32_e32 v0, v248
	s_lshl_b32 s8, s12, 6
	s_and_b32 s8, s8, 0xfc0
	v_readlane_b32 s76, v250, 16
	v_and_b32_e32 v1, 63, v0
	v_ashrrev_i32_e32 v0, 6, v0
	s_lshl_b32 s9, s8, 2
	v_readlane_b32 s86, v250, 26
	v_readlane_b32 s87, v250, 27
	s_add_u32 s14, s86, s9
	v_add_u32_e32 v4, s26, v0
	s_addc_u32 s15, s87, 0
	v_lshlrev_b32_e32 v74, 2, v1
	v_ashrrev_i32_e32 v5, 31, v4
	v_lshl_add_u64 v[2:3], s[14:15], 0, v[74:75]
	v_lshlrev_b64 v[6:7], 14, v[4:5]
	v_lshl_add_u64 v[6:7], v[2:3], 0, v[6:7]
	s_waitcnt lgkmcnt(0)
	s_barrier
	global_load_dword v218, v[6:7], off
	v_readlane_b32 s88, v250, 28
	v_readlane_b32 s88, v250, 35
	v_mul_lo_u32 v6, v0, s57
	s_lshl_b64 s[14:15], s[26:27], 1
	v_add3_u32 v8, s88, v6, v74
	v_add_u32_e32 v6, 4, v4
	v_ashrrev_i32_e32 v7, 31, v6
	v_lshlrev_b64 v[6:7], 14, v[6:7]
	v_lshl_add_u64 v[6:7], v[2:3], 0, v[6:7]
	v_readlane_b32 s84, v250, 24
	v_readlane_b32 s85, v250, 25
	s_add_u32 s14, s67, s14
	v_readlane_b32 s84, v250, 33
	s_addc_u32 s15, s68, s15
	v_lshlrev_b32_e32 v74, 1, v1
	v_readlane_b32 s85, v250, 34
	s_mov_b32 s9, 16
	s_mov_b32 s13, 1
	v_readlane_b32 s77, v250, 17
	v_readlane_b32 s78, v250, 18
	v_readlane_b32 s79, v250, 19
	v_readlane_b32 s80, v250, 20
	v_readlane_b32 s81, v250, 21
	v_readlane_b32 s82, v250, 22
	v_readlane_b32 s83, v250, 23
	v_readlane_b32 s89, v250, 29
	v_readlane_b32 s90, v250, 30
	v_readlane_b32 s91, v250, 31
	global_load_dword v219, v[6:7], off
	v_add_u32_e32 v6, 8, v4
	v_ashrrev_i32_e32 v7, 31, v6
	v_lshlrev_b64 v[6:7], 14, v[6:7]
	v_lshl_add_u64 v[6:7], v[2:3], 0, v[6:7]
	global_load_dword v220, v[6:7], off
	v_add_u32_e32 v6, 12, v4
	v_ashrrev_i32_e32 v7, 31, v6
	v_lshlrev_b64 v[6:7], 14, v[6:7]
	v_lshl_add_u64 v[6:7], v[2:3], 0, v[6:7]
	global_load_dword v221, v[6:7], off
	v_add_u32_e32 v6, 16, v4
	v_ashrrev_i32_e32 v7, 31, v6
	v_lshlrev_b64 v[6:7], 14, v[6:7]
	v_lshl_add_u64 v[6:7], v[2:3], 0, v[6:7]
	global_load_dword v222, v[6:7], off
	v_add_u32_e32 v6, 20, v4
	v_ashrrev_i32_e32 v7, 31, v6
	v_lshlrev_b64 v[6:7], 14, v[6:7]
	v_lshl_add_u64 v[6:7], v[2:3], 0, v[6:7]
	global_load_dword v223, v[6:7], off
	v_add_u32_e32 v6, 24, v4
	v_ashrrev_i32_e32 v7, 31, v6
	v_lshlrev_b64 v[6:7], 14, v[6:7]
	v_lshl_add_u64 v[6:7], v[2:3], 0, v[6:7]
	global_load_dword v224, v[6:7], off
	v_add_u32_e32 v6, 28, v4
	v_ashrrev_i32_e32 v7, 31, v6
	v_lshlrev_b64 v[6:7], 14, v[6:7]
	v_lshl_add_u64 v[6:7], v[2:3], 0, v[6:7]
	global_load_dword v225, v[6:7], off
	v_add_u32_e32 v6, 32, v4
	v_ashrrev_i32_e32 v7, 31, v6
	v_lshlrev_b64 v[6:7], 14, v[6:7]
	v_lshl_add_u64 v[6:7], v[2:3], 0, v[6:7]
	global_load_dword v226, v[6:7], off
	v_add_u32_e32 v6, 36, v4
	v_ashrrev_i32_e32 v7, 31, v6
	v_lshlrev_b64 v[6:7], 14, v[6:7]
	v_lshl_add_u64 v[6:7], v[2:3], 0, v[6:7]
	global_load_dword v227, v[6:7], off
	v_add_u32_e32 v6, 40, v4
	v_ashrrev_i32_e32 v7, 31, v6
	v_lshlrev_b64 v[6:7], 14, v[6:7]
	v_lshl_add_u64 v[6:7], v[2:3], 0, v[6:7]
	global_load_dword v228, v[6:7], off
	v_add_u32_e32 v6, 44, v4
	v_ashrrev_i32_e32 v7, 31, v6
	v_lshlrev_b64 v[6:7], 14, v[6:7]
	v_lshl_add_u64 v[6:7], v[2:3], 0, v[6:7]
	global_load_dword v229, v[6:7], off
	v_add_u32_e32 v6, 48, v4
	v_ashrrev_i32_e32 v7, 31, v6
	v_lshlrev_b64 v[6:7], 14, v[6:7]
	v_lshl_add_u64 v[6:7], v[2:3], 0, v[6:7]
	global_load_dword v230, v[6:7], off
	v_add_u32_e32 v6, 52, v4
	v_ashrrev_i32_e32 v7, 31, v6
	v_lshlrev_b64 v[6:7], 14, v[6:7]
	v_lshl_add_u64 v[6:7], v[2:3], 0, v[6:7]
	global_load_dword v231, v[6:7], off
	v_add_u32_e32 v6, 56, v4
	v_ashrrev_i32_e32 v7, 31, v6
	v_lshlrev_b64 v[6:7], 14, v[6:7]
	v_lshl_add_u64 v[6:7], v[2:3], 0, v[6:7]
	v_add_u32_e32 v4, 60, v4
	global_load_dword v232, v[6:7], off
	v_add_u32_e32 v6, 16, v0
	v_mov_b32_e32 v7, v6
	v_ashrrev_i32_e32 v5, 31, v4
	v_lshlrev_b64 v[4:5], 14, v[4:5]
	v_lshl_add_u64 v[2:3], v[2:3], 0, v[4:5]
	global_load_dword v233, v[2:3], off
	v_mov_b32_e32 v4, s88
	v_mad_u32_u24 v10, v1, s57, v4
	v_add_u32_e32 v4, 8, v0
	v_mov_b32_e32 v1, v0
	v_mov_b32_e32 v5, v4
	s_waitcnt vmcnt(15)
	ds_write_b32 v8, v218
	s_waitcnt vmcnt(14)
	ds_write_b32 v8, v219 offset:1040
	s_waitcnt vmcnt(13)
	ds_write_b32 v8, v220 offset:2080
	s_waitcnt vmcnt(12)
	ds_write_b32 v8, v221 offset:3120
	s_waitcnt vmcnt(11)
	ds_write_b32 v8, v222 offset:4160
	s_waitcnt vmcnt(10)
	ds_write_b32 v8, v223 offset:5200
	s_waitcnt vmcnt(9)
	ds_write_b32 v8, v224 offset:6240
	s_waitcnt vmcnt(8)
	ds_write_b32 v8, v225 offset:7280
	s_waitcnt vmcnt(7)
	ds_write_b32 v8, v226 offset:8320
	s_waitcnt vmcnt(6)
	ds_write_b32 v8, v227 offset:9360
	s_waitcnt vmcnt(5)
	ds_write_b32 v8, v228 offset:10400
	s_waitcnt vmcnt(4)
	ds_write_b32 v8, v229 offset:11440
	s_waitcnt vmcnt(3)
	ds_write_b32 v8, v230 offset:12480
	s_waitcnt vmcnt(2)
	ds_write_b32 v8, v231 offset:13520
	s_waitcnt vmcnt(1)
	ds_write_b32 v8, v232 offset:14560
	s_waitcnt vmcnt(0)
	ds_write_b32 v8, v233 offset:15600
	v_add_u32_e32 v8, 24, v0
	v_lshl_add_u64 v[2:3], s[14:15], 0, v[74:75]
	s_mov_b32 s14, s8
	v_mov_b32_e32 v9, v8
	s_mov_b32 s15, 0
	s_waitcnt lgkmcnt(0)
	s_barrier

; DI void wtrans_tile(const float* __restrict__ src, int K, int N, u16* __restrict__ dst, int ldw, int tk, int tn,
;                     const float* __restrict__ kscale, char* lds) {
;     ...
;   const int tid = tid_, j = tid & 63, i0 = tid >> 6;
;   const int k0 = tk * 64, n0 = tn * 64;
;   __syncthreads();
; #pragma unroll
;   for (int q = 0; q < 16; ++q) {
;     int i = i0 + 4 * q;
;     float v = (n0 + j < N) ? src[(size_t)(k0 + i) * N + n0 + j] : 0.f;
;     if (kscale) v *= kscale[k0 + i];
;     t[i * 65 + j] = v;
;   }
.LBB0_127:
	s_andn2_b64 vcc, exec, s[8:9]
	s_cbranch_vccnz .LBB0_130
	s_lshl_b32 s8, s12, 2
	s_and_b32 s8, s8, 0xfc0
	v_mov_b32_e32 v0, v248
	s_add_i32 s26, s8, 0xfffff500
	s_lshl_b32 s8, s12, 6
	s_and_b32 s8, s8, 0x3c0
	v_readlane_b32 s76, v250, 16
	v_and_b32_e32 v1, 63, v0
	v_ashrrev_i32_e32 v0, 6, v0
	s_lshl_b32 s9, s8, 2
	v_readlane_b32 s80, v250, 20
	v_readlane_b32 s81, v250, 21
	s_add_u32 s14, s80, s9
	v_add_u32_e32 v4, s26, v0
	s_addc_u32 s15, s81, 0
	v_lshlrev_b32_e32 v74, 2, v1
	v_ashrrev_i32_e32 v5, 31, v4
	v_lshl_add_u64 v[2:3], s[14:15], 0, v[74:75]
	v_lshlrev_b64 v[6:7], 12, v[4:5]
	v_lshl_add_u64 v[6:7], v[2:3], 0, v[6:7]
	s_waitcnt lgkmcnt(0)
	s_barrier
	global_load_dword v218, v[6:7], off
	v_readlane_b32 s88, v250, 28
	v_readlane_b32 s88, v250, 35
	v_mul_lo_u32 v6, v0, s57
	s_lshl_b64 s[14:15], s[26:27], 1
	v_add3_u32 v8, s88, v6, v74
	v_add_u32_e32 v6, 4, v4
	v_ashrrev_i32_e32 v7, 31, v6
	v_lshlrev_b64 v[6:7], 12, v[6:7]
	v_lshl_add_u64 v[6:7], v[2:3], 0, v[6:7]
	v_readlane_b32 s84, v250, 24
	v_readlane_b32 s85, v250, 25
	s_add_u32 s14, s69, s14
	v_readlane_b32 s84, v250, 33
	s_addc_u32 s15, s70, s15
	v_lshlrev_b32_e32 v74, 1, v1
	v_readlane_b32 s85, v250, 34
	s_mov_b32 s9, 16
	s_mov_b32 s13, 1
	v_readlane_b32 s77, v250, 17
	v_readlane_b32 s78, v250, 18
	v_readlane_b32 s79, v250, 19
	v_readlane_b32 s82, v250, 22
	v_readlane_b32 s83, v250, 23
	v_readlane_b32 s86, v250, 26
	v_readlane_b32 s87, v250, 27
	v_readlane_b32 s89, v250, 29
	v_readlane_b32 s90, v250, 30
	v_readlane_b32 s91, v250, 31
	global_load_dword v219, v[6:7], off
	v_add_u32_e32 v6, 8, v4
	v_ashrrev_i32_e32 v7, 31, v6
	v_lshlrev_b64 v[6:7], 12, v[6:7]
	v_lshl_add_u64 v[6:7], v[2:3], 0, v[6:7]
	global_load_dword v220, v[6:7], off
	v_add_u32_e32 v6, 12, v4
	v_ashrrev_i32_e32 v7, 31, v6
	v_lshlrev_b64 v[6:7], 12, v[6:7]
	v_lshl_add_u64 v[6:7], v[2:3], 0, v[6:7]
	global_load_dword v221, v[6:7], off
	v_add_u32_e32 v6, 16, v4
	v_ashrrev_i32_e32 v7, 31, v6
	v_lshlrev_b64 v[6:7], 12, v[6:7]
	v_lshl_add_u64 v[6:7], v[2:3], 0, v[6:7]
	global_load_dword v222, v[6:7], off
	v_add_u32_e32 v6, 20, v4
	v_ashrrev_i32_e32 v7, 31, v6
	v_lshlrev_b64 v[6:7], 12, v[6:7]
	v_lshl_add_u64 v[6:7], v[2:3], 0, v[6:7]
	global_load_dword v223, v[6:7], off
	v_add_u32_e32 v6, 24, v4
	v_ashrrev_i32_e32 v7, 31, v6
	v_lshlrev_b64 v[6:7], 12, v[6:7]
	v_lshl_add_u64 v[6:7], v[2:3], 0, v[6:7]
	global_load_dword v224, v[6:7], off
	v_add_u32_e32 v6, 28, v4
	v_ashrrev_i32_e32 v7, 31, v6
	v_lshlrev_b64 v[6:7], 12, v[6:7]
	v_lshl_add_u64 v[6:7], v[2:3], 0, v[6:7]
	global_load_dword v225, v[6:7], off
	v_add_u32_e32 v6, 32, v4
	v_ashrrev_i32_e32 v7, 31, v6
	v_lshlrev_b64 v[6:7], 12, v[6:7]
	v_lshl_add_u64 v[6:7], v[2:3], 0, v[6:7]
	global_load_dword v226, v[6:7], off
	v_add_u32_e32 v6, 36, v4
	v_ashrrev_i32_e32 v7, 31, v6
	v_lshlrev_b64 v[6:7], 12, v[6:7]
	v_lshl_add_u64 v[6:7], v[2:3], 0, v[6:7]
	global_load_dword v227, v[6:7], off
	v_add_u32_e32 v6, 40, v4
	v_ashrrev_i32_e32 v7, 31, v6
	v_lshlrev_b64 v[6:7], 12, v[6:7]
	v_lshl_add_u64 v[6:7], v[2:3], 0, v[6:7]
	global_load_dword v228, v[6:7], off
	v_add_u32_e32 v6, 44, v4
	v_ashrrev_i32_e32 v7, 31, v6
	v_lshlrev_b64 v[6:7], 12, v[6:7]
	v_lshl_add_u64 v[6:7], v[2:3], 0, v[6:7]
	global_load_dword v229, v[6:7], off
	v_add_u32_e32 v6, 48, v4
	v_ashrrev_i32_e32 v7, 31, v6
	v_lshlrev_b64 v[6:7], 12, v[6:7]
	v_lshl_add_u64 v[6:7], v[2:3], 0, v[6:7]
	global_load_dword v230, v[6:7], off
	v_add_u32_e32 v6, 52, v4
	v_ashrrev_i32_e32 v7, 31, v6
	v_lshlrev_b64 v[6:7], 12, v[6:7]
	v_lshl_add_u64 v[6:7], v[2:3], 0, v[6:7]
	global_load_dword v231, v[6:7], off
	v_add_u32_e32 v6, 56, v4
	v_ashrrev_i32_e32 v7, 31, v6
	v_lshlrev_b64 v[6:7], 12, v[6:7]
	v_lshl_add_u64 v[6:7], v[2:3], 0, v[6:7]
	v_add_u32_e32 v4, 60, v4
	global_load_dword v232, v[6:7], off
	v_add_u32_e32 v6, 16, v0
	v_mov_b32_e32 v7, v6
	v_ashrrev_i32_e32 v5, 31, v4
	v_lshlrev_b64 v[4:5], 12, v[4:5]
	v_lshl_add_u64 v[2:3], v[2:3], 0, v[4:5]
	global_load_dword v233, v[2:3], off
	v_mov_b32_e32 v4, s88
	v_mad_u32_u24 v10, v1, s57, v4
	v_add_u32_e32 v4, 8, v0
	v_mov_b32_e32 v1, v0
	v_mov_b32_e32 v5, v4
	s_waitcnt vmcnt(15)
	ds_write_b32 v8, v218
	s_waitcnt vmcnt(14)
	ds_write_b32 v8, v219 offset:1040
	s_waitcnt vmcnt(13)
	ds_write_b32 v8, v220 offset:2080
	s_waitcnt vmcnt(12)
	ds_write_b32 v8, v221 offset:3120
	s_waitcnt vmcnt(11)
	ds_write_b32 v8, v222 offset:4160
	s_waitcnt vmcnt(10)
	ds_write_b32 v8, v223 offset:5200
	s_waitcnt vmcnt(9)
	ds_write_b32 v8, v224 offset:6240
	s_waitcnt vmcnt(8)
	ds_write_b32 v8, v225 offset:7280
	s_waitcnt vmcnt(7)
	ds_write_b32 v8, v226 offset:8320
	s_waitcnt vmcnt(6)
	ds_write_b32 v8, v227 offset:9360
	s_waitcnt vmcnt(5)
	ds_write_b32 v8, v228 offset:10400
	s_waitcnt vmcnt(4)
	ds_write_b32 v8, v229 offset:11440
	s_waitcnt vmcnt(3)
	ds_write_b32 v8, v230 offset:12480
	s_waitcnt vmcnt(2)
	ds_write_b32 v8, v231 offset:13520
	s_waitcnt vmcnt(1)
	ds_write_b32 v8, v232 offset:14560
	s_waitcnt vmcnt(0)
	ds_write_b32 v8, v233 offset:15600
	v_add_u32_e32 v8, 24, v0
	v_lshl_add_u64 v[2:3], s[14:15], 0, v[74:75]
	s_mov_b32 s14, s8
	v_mov_b32_e32 v9, v8
	s_mov_b32 s15, 0
	s_waitcnt lgkmcnt(0)
	s_barrier

; DI void prep_mla(const Params& p, int layer, int tm, int which, int nt, char* lds) {
;     ...
;       for (int idx = tid; idx < 128 * 32; idx += 256) {
;         const int rr = idx >> 5, c4 = (idx & 31) * 4;
;         const int row = m0 + half * 128 + rr;
;         const float sc = rs[half * 128 + rr] * qs;
;         float o[4];
; #pragma unroll
;         for (int j = 0; j < 4; ++j) {
;           int cl = c4 + j, c = nt * 128 + cl, d = c % 96;
;           float v = Cs[rr * CSL + cl];
;           if (d >= 64 && row < NLAT) {
;             int i = d - 64;
;             if (i < 16) {
;               float2 t = tab[(row & 4095) * 64 + 48 + i];
;               float x2 = Cs[rr * CSL + cl + 16];
;               v = v * t.x - x2 * t.y;
;             } else {
;               float2 t = tab[(row & 4095) * 64 + 48 + i - 16];
;               float x1 = Cs[rr * CSL + cl - 16];
;               v = x1 * t.y + v * t.x;
;             }
;           }
;           o[j] = v * sc;
;         }
;         uint2 w;
;         w.x = pack2(o[0], o[1]); w.y = pack2(o[2], o[3]);
;         *(uint2*)(QD + (size_t)row * 384 + nt * 128 + c4) = w;
;       }
.LBB0_251:
	v_ashrrev_i32_e32 v130, 5, v143
	v_add_u32_e32 v0, s31, v130
	v_add_u32_e32 v145, s26, v0
	v_lshl_add_u32 v0, v0, 2, s19
	v_and_b32_e32 v144, 0x7c, v142
	ds_read_b32 v146, v0
	v_lshlrev_b32_e32 v0, 6, v145
	v_and_b32_e32 v138, 0x3ffc0, v0
	v_or_b32_e32 v0, s27, v144
	s_mov_b32 s2, 0x2aaaaab
	v_mul_hi_u32 v131, v0, s2
	v_mul_u32_u24_e32 v131, 0x60, v131
	s_movk_i32 s2, 0x210
	v_sub_u32_e32 v0, v0, v131
	v_lshlrev_b32_e32 v131, 2, v144
	v_mul_lo_u32 v130, v130, s2
	v_add3_u32 v147, s88, v131, v130
	ds_read_b128 v[170:173], v147
	v_cmp_gt_i32_e32 vcc, s55, v145
	v_cmp_lt_u32_e64 s[2:3], 63, v0
	s_and_b64 s[2:3], s[2:3], vcc
	s_and_saveexec_b64 s[16:17], s[2:3]
	s_cbranch_execz .Lprepq_norot
	s_movk_i32 s2, 0x4f
	v_cmp_lt_u32_e64 s[2:3], s2, v0
	v_readlane_b32 s20, v250, 59
	v_readlane_b32 s21, v250, 60
	v_mov_b32_e32 v161, 0xffffffe0
	v_cndmask_b32_e64 v160, -16, v161, s[2:3]
	v_add3_u32 v0, v138, v0, v160
	v_lshl_add_u64 v[156:157], v[0:1], 3, s[20:21]
	global_load_dwordx4 v[148:151], v[156:157], off
	global_load_dwordx4 v[152:155], v[156:157], off offset:16
	v_mov_b32_e32 v161, 0xffffffc0
	v_cndmask_b32_e64 v160, 64, v161, s[2:3]
	v_add_u32_e32 v160, v147, v160
	ds_read_b128 v[166:169], v160
	s_waitcnt vmcnt(0) lgkmcnt(0)
	v_mul_f32_e32 v161, v166, v149
	v_mul_f32_e32 v170, v170, v148
	v_cndmask_b32_e64 v161, -v161, v161, s[2:3]
	v_add_f32_e32 v170, v170, v161
	v_mul_f32_e32 v161, v167, v151
	v_mul_f32_e32 v171, v171, v150
	v_cndmask_b32_e64 v161, -v161, v161, s[2:3]
	v_add_f32_e32 v171, v171, v161
	v_mul_f32_e32 v161, v168, v153
	v_mul_f32_e32 v172, v172, v152
	v_cndmask_b32_e64 v161, -v161, v161, s[2:3]
	v_add_f32_e32 v172, v172, v161
	v_mul_f32_e32 v161, v169, v155
	v_mul_f32_e32 v173, v173, v154
	v_cndmask_b32_e64 v161, -v161, v161, s[2:3]
	v_add_f32_e32 v173, v173, v161
.Lprepq_norot:
	s_or_b64 exec, exec, s[16:17]
	s_waitcnt lgkmcnt(0)
	v_mul_f32_e32 v0, 0x3e16c740, v146
	v_mul_f32_e32 v130, v0, v170
	v_mul_f32_e32 v132, v0, v171
	v_cvt_pk_bf16_f32 v130, v130, v132
	v_mov_b64_e32 v[132:133], s[8:9]
	s_movk_i32 s2, 0x300
	v_mul_f32_e32 v131, v0, v172
	v_mul_f32_e32 v0, v0, v173
	v_mad_i64_i32 v[132:133], s[2:3], v145, s2, v[132:133]
	v_cvt_pk_bf16_f32 v131, v131, v0
	v_lshlrev_b32_e32 v0, 1, v144
	s_movk_i32 s2, 0xeff
	v_lshl_add_u64 v[132:133], v[132:133], 0, v[0:1]
	v_add_u32_e32 v0, 0x100, v143
	v_cmp_lt_i32_e32 vcc, s2, v143
	v_add_u32_e32 v142, 0x400, v142
	s_or_b64 s[14:15], vcc, s[14:15]
	v_mov_b32_e32 v143, v0
	global_store_dwordx2 v[132:133], v[130:131], off
	s_andn2_b64 exec, exec, s[14:15]
	s_cbranch_execnz .LBB0_251
	s_branch .LBB0_244

; DI void wtrans_tile(const float* __restrict__ src, int K, int N, u16* __restrict__ dst, int ldw, int tk, int tn,
;                     const float* __restrict__ kscale, char* lds) {
;     ...
;   const int tid = tid_, j = tid & 63, i0 = tid >> 6;
;   const int k0 = tk * 64, n0 = tn * 64;
;   __syncthreads();
; #pragma unroll
;   for (int q = 0; q < 16; ++q) {
;     int i = i0 + 4 * q;
;     float v = (n0 + j < N) ? src[(size_t)(k0 + i) * N + n0 + j] : 0.f;
;     if (kscale) v *= kscale[k0 + i];
;     t[i * 65 + j] = v;
;   }
.LBB0_489:
	s_andn2_b64 vcc, exec, s[0:1]
	s_movk_i32 s11, 0x2100
	s_cbranch_vccnz .LBB0_492
	s_lshl_b32 s0, s3, 2
	s_and_b32 s0, s0, 0x3fc0
	v_readlane_b32 s6, v252, 20
	s_add_i32 s6, s0, 0xffffe100
	s_lshl_b32 s0, s3, 6
	v_mov_b32_e32 v0, v248
	s_and_b32 s0, s0, 0x3c0
	s_lshl_b32 s1, s0, 2
	v_ashrrev_i32_e32 v2, 6, v0
	v_readlane_b32 s4, v251, 24
	v_and_b32_e32 v3, 63, v0
	s_add_u32 s4, s4, s1
	v_readlane_b32 s1, v251, 25
	v_add_u32_e32 v6, s6, v2
	s_addc_u32 s5, s1, 0
	v_lshlrev_b32_e32 v0, 2, v3
	v_ashrrev_i32_e32 v7, 31, v6
	v_lshl_add_u64 v[4:5], s[4:5], 0, v[0:1]
	v_lshlrev_b64 v[8:9], 12, v[6:7]
	v_lshl_add_u64 v[8:9], v[4:5], 0, v[8:9]
	s_barrier
	global_load_dword v218, v[8:9], off
	s_movk_i32 s8, 0x104
	v_mul_lo_u32 v8, v2, s8
	v_add3_u32 v0, s88, v8, v0
	v_add_u32_e32 v8, 4, v6
	v_ashrrev_i32_e32 v9, 31, v8
	v_lshlrev_b64 v[8:9], 12, v[8:9]
	v_lshl_add_u64 v[8:9], v[4:5], 0, v[8:9]
	v_readlane_b32 s7, v252, 21
	s_mov_b32 s4, 1
	s_mov_b32 s5, s7
	v_writelane_b32 v252, s4, 20
	s_lshl_b64 s[6:7], s[6:7], 1
	s_mov_b32 s1, 16
	v_writelane_b32 v252, s5, 21
	v_readlane_b32 s5, v251, 26
	s_add_u32 s6, s5, s6
	v_readlane_b32 s5, v251, 27
	s_addc_u32 s7, s5, s7
	s_mov_b32 s5, s0
	global_load_dword v219, v[8:9], off
	v_add_u32_e32 v8, 8, v6
	v_ashrrev_i32_e32 v9, 31, v8
	v_lshlrev_b64 v[8:9], 12, v[8:9]
	v_lshl_add_u64 v[8:9], v[4:5], 0, v[8:9]
	global_load_dword v220, v[8:9], off
	v_add_u32_e32 v8, 12, v6
	v_ashrrev_i32_e32 v9, 31, v8
	v_lshlrev_b64 v[8:9], 12, v[8:9]
	v_lshl_add_u64 v[8:9], v[4:5], 0, v[8:9]
	global_load_dword v221, v[8:9], off
	v_add_u32_e32 v8, 16, v6
	v_ashrrev_i32_e32 v9, 31, v8
	v_lshlrev_b64 v[8:9], 12, v[8:9]
	v_lshl_add_u64 v[8:9], v[4:5], 0, v[8:9]
	global_load_dword v222, v[8:9], off
	v_add_u32_e32 v8, 20, v6
	v_ashrrev_i32_e32 v9, 31, v8
	v_lshlrev_b64 v[8:9], 12, v[8:9]
	v_lshl_add_u64 v[8:9], v[4:5], 0, v[8:9]
	global_load_dword v223, v[8:9], off
	v_add_u32_e32 v8, 24, v6
	v_ashrrev_i32_e32 v9, 31, v8
	v_lshlrev_b64 v[8:9], 12, v[8:9]
	v_lshl_add_u64 v[8:9], v[4:5], 0, v[8:9]
	global_load_dword v224, v[8:9], off
	v_add_u32_e32 v8, 28, v6
	v_ashrrev_i32_e32 v9, 31, v8
	v_lshlrev_b64 v[8:9], 12, v[8:9]
	v_lshl_add_u64 v[8:9], v[4:5], 0, v[8:9]
	global_load_dword v225, v[8:9], off
	v_add_u32_e32 v8, 32, v6
	v_ashrrev_i32_e32 v9, 31, v8
	v_lshlrev_b64 v[8:9], 12, v[8:9]
	v_lshl_add_u64 v[8:9], v[4:5], 0, v[8:9]
	global_load_dword v226, v[8:9], off
	v_add_u32_e32 v8, 36, v6
	v_ashrrev_i32_e32 v9, 31, v8
	v_lshlrev_b64 v[8:9], 12, v[8:9]
	v_lshl_add_u64 v[8:9], v[4:5], 0, v[8:9]
	global_load_dword v227, v[8:9], off
	v_add_u32_e32 v8, 40, v6
	v_ashrrev_i32_e32 v9, 31, v8
	v_lshlrev_b64 v[8:9], 12, v[8:9]
	v_lshl_add_u64 v[8:9], v[4:5], 0, v[8:9]
	global_load_dword v228, v[8:9], off
	v_add_u32_e32 v8, 44, v6
	v_ashrrev_i32_e32 v9, 31, v8
	v_lshlrev_b64 v[8:9], 12, v[8:9]
	v_lshl_add_u64 v[8:9], v[4:5], 0, v[8:9]
	global_load_dword v229, v[8:9], off
	v_add_u32_e32 v8, 48, v6
	v_ashrrev_i32_e32 v9, 31, v8
	v_lshlrev_b64 v[8:9], 12, v[8:9]
	v_lshl_add_u64 v[8:9], v[4:5], 0, v[8:9]
	global_load_dword v230, v[8:9], off
	v_add_u32_e32 v8, 52, v6
	v_ashrrev_i32_e32 v9, 31, v8
	v_lshlrev_b64 v[8:9], 12, v[8:9]
	v_lshl_add_u64 v[8:9], v[4:5], 0, v[8:9]
	global_load_dword v231, v[8:9], off
	v_add_u32_e32 v8, 56, v6
	v_ashrrev_i32_e32 v9, 31, v8
	v_lshlrev_b64 v[8:9], 12, v[8:9]
	v_lshl_add_u64 v[8:9], v[4:5], 0, v[8:9]
	v_add_u32_e32 v6, 60, v6
	global_load_dword v232, v[8:9], off
	v_add_u32_e32 v8, 24, v2
	v_mov_b32_e32 v11, v8
	v_ashrrev_i32_e32 v7, 31, v6
	v_lshlrev_b64 v[6:7], 12, v[6:7]
	v_lshl_add_u64 v[4:5], v[4:5], 0, v[6:7]
	global_load_dword v233, v[4:5], off
	v_add_u32_e32 v6, 16, v2
	v_mov_b32_e32 v9, v6
	s_waitcnt vmcnt(15)
	ds_write_b32 v0, v218
	s_waitcnt vmcnt(14)
	ds_write_b32 v0, v219 offset:1040
	s_waitcnt vmcnt(13)
	ds_write_b32 v0, v220 offset:2080
	s_waitcnt vmcnt(12)
	ds_write_b32 v0, v221 offset:3120
	s_waitcnt vmcnt(11)
	ds_write_b32 v0, v222 offset:4160
	s_waitcnt vmcnt(10)
	ds_write_b32 v0, v223 offset:5200
	s_waitcnt vmcnt(9)
	ds_write_b32 v0, v224 offset:6240
	s_waitcnt vmcnt(8)
	ds_write_b32 v0, v225 offset:7280
	s_waitcnt vmcnt(7)
	ds_write_b32 v0, v226 offset:8320
	s_waitcnt vmcnt(6)
	ds_write_b32 v0, v227 offset:9360
	s_waitcnt vmcnt(5)
	ds_write_b32 v0, v228 offset:10400
	s_waitcnt vmcnt(4)
	ds_write_b32 v0, v229 offset:11440
	s_waitcnt vmcnt(3)
	ds_write_b32 v0, v230 offset:12480
	s_waitcnt vmcnt(2)
	ds_write_b32 v0, v231 offset:13520
	s_waitcnt vmcnt(1)
	ds_write_b32 v0, v232 offset:14560
	s_waitcnt vmcnt(0)
	ds_write_b32 v0, v233 offset:15600
	v_lshlrev_b32_e32 v0, 1, v3
	v_lshl_add_u64 v[4:5], s[6:7], 0, v[0:1]
	v_mov_b32_e32 v0, s88
	v_mad_u32_u24 v10, v3, s8, v0
	v_add_u32_e32 v0, 8, v2
	v_mov_b32_e32 v3, v2
	v_mov_b32_e32 v7, v0
	s_mov_b32 s6, 0
	s_waitcnt lgkmcnt(0)
	s_barrier

; DI void wtrans_tile(const float* __restrict__ src, int K, int N, u16* __restrict__ dst, int ldw, int tk, int tn,
;                     const float* __restrict__ kscale, char* lds) {
;     ...
;   const int tid = tid_, j = tid & 63, i0 = tid >> 6;
;   const int k0 = tk * 64, n0 = tn * 64;
;   __syncthreads();
; #pragma unroll
;   for (int q = 0; q < 16; ++q) {
;     int i = i0 + 4 * q;
;     float v = (n0 + j < N) ? src[(size_t)(k0 + i) * N + n0 + j] : 0.f;
;     if (kscale) v *= kscale[k0 + i];
;     t[i * 65 + j] = v;
;   }
.LBB0_493:
	s_andn2_b64 vcc, exec, s[0:1]
	s_movk_i32 s11, 0x900
	s_cbranch_vccnz .LBB0_496
	s_and_b32 s0, s3, 0x7c0
	v_readlane_b32 s6, v252, 20
	s_add_i32 s6, s0, 0xfffffc40
	s_lshl_b32 s0, s3, 6
	v_mov_b32_e32 v0, v248
	s_and_b32 s0, s0, 0xfc0
	s_lshl_b32 s1, s0, 2
	v_ashrrev_i32_e32 v2, 6, v0
	v_readlane_b32 s4, v251, 28
	v_and_b32_e32 v3, 63, v0
	s_add_u32 s4, s4, s1
	v_readlane_b32 s1, v251, 29
	v_add_u32_e32 v6, s6, v2
	s_addc_u32 s5, s1, 0
	v_lshlrev_b32_e32 v0, 2, v3
	v_ashrrev_i32_e32 v7, 31, v6
	v_lshl_add_u64 v[4:5], s[4:5], 0, v[0:1]
	v_lshlrev_b64 v[8:9], 14, v[6:7]
	v_lshl_add_u64 v[8:9], v[4:5], 0, v[8:9]
	s_barrier
	global_load_dword v218, v[8:9], off
	s_movk_i32 s8, 0x104
	v_mul_lo_u32 v8, v2, s8
	v_add3_u32 v0, s88, v8, v0
	v_add_u32_e32 v8, 4, v6
	v_ashrrev_i32_e32 v9, 31, v8
	v_lshlrev_b64 v[8:9], 14, v[8:9]
	v_lshl_add_u64 v[8:9], v[4:5], 0, v[8:9]
	v_readlane_b32 s7, v252, 21
	s_mov_b32 s4, 1
	s_mov_b32 s5, s7
	v_writelane_b32 v252, s4, 20
	s_lshl_b64 s[6:7], s[6:7], 1
	s_mov_b32 s1, 16
	v_writelane_b32 v252, s5, 21
	v_readlane_b32 s5, v251, 30
	s_add_u32 s6, s5, s6
	v_readlane_b32 s5, v251, 31
	s_addc_u32 s7, s5, s7
	s_mov_b32 s5, s0
	global_load_dword v219, v[8:9], off
	v_add_u32_e32 v8, 8, v6
	v_ashrrev_i32_e32 v9, 31, v8
	v_lshlrev_b64 v[8:9], 14, v[8:9]
	v_lshl_add_u64 v[8:9], v[4:5], 0, v[8:9]
	global_load_dword v220, v[8:9], off
	v_add_u32_e32 v8, 12, v6
	v_ashrrev_i32_e32 v9, 31, v8
	v_lshlrev_b64 v[8:9], 14, v[8:9]
	v_lshl_add_u64 v[8:9], v[4:5], 0, v[8:9]
	global_load_dword v221, v[8:9], off
	v_add_u32_e32 v8, 16, v6
	v_ashrrev_i32_e32 v9, 31, v8
	v_lshlrev_b64 v[8:9], 14, v[8:9]
	v_lshl_add_u64 v[8:9], v[4:5], 0, v[8:9]
	global_load_dword v222, v[8:9], off
	v_add_u32_e32 v8, 20, v6
	v_ashrrev_i32_e32 v9, 31, v8
	v_lshlrev_b64 v[8:9], 14, v[8:9]
	v_lshl_add_u64 v[8:9], v[4:5], 0, v[8:9]
	global_load_dword v223, v[8:9], off
	v_add_u32_e32 v8, 24, v6
	v_ashrrev_i32_e32 v9, 31, v8
	v_lshlrev_b64 v[8:9], 14, v[8:9]
	v_lshl_add_u64 v[8:9], v[4:5], 0, v[8:9]
	global_load_dword v224, v[8:9], off
	v_add_u32_e32 v8, 28, v6
	v_ashrrev_i32_e32 v9, 31, v8
	v_lshlrev_b64 v[8:9], 14, v[8:9]
	v_lshl_add_u64 v[8:9], v[4:5], 0, v[8:9]
	global_load_dword v225, v[8:9], off
	v_add_u32_e32 v8, 32, v6
	v_ashrrev_i32_e32 v9, 31, v8
	v_lshlrev_b64 v[8:9], 14, v[8:9]
	v_lshl_add_u64 v[8:9], v[4:5], 0, v[8:9]
	global_load_dword v226, v[8:9], off
	v_add_u32_e32 v8, 36, v6
	v_ashrrev_i32_e32 v9, 31, v8
	v_lshlrev_b64 v[8:9], 14, v[8:9]
	v_lshl_add_u64 v[8:9], v[4:5], 0, v[8:9]
	global_load_dword v227, v[8:9], off
	v_add_u32_e32 v8, 40, v6
	v_ashrrev_i32_e32 v9, 31, v8
	v_lshlrev_b64 v[8:9], 14, v[8:9]
	v_lshl_add_u64 v[8:9], v[4:5], 0, v[8:9]
	global_load_dword v228, v[8:9], off
	v_add_u32_e32 v8, 44, v6
	v_ashrrev_i32_e32 v9, 31, v8
	v_lshlrev_b64 v[8:9], 14, v[8:9]
	v_lshl_add_u64 v[8:9], v[4:5], 0, v[8:9]
	global_load_dword v229, v[8:9], off
	v_add_u32_e32 v8, 48, v6
	v_ashrrev_i32_e32 v9, 31, v8
	v_lshlrev_b64 v[8:9], 14, v[8:9]
	v_lshl_add_u64 v[8:9], v[4:5], 0, v[8:9]
	global_load_dword v230, v[8:9], off
	v_add_u32_e32 v8, 52, v6
	v_ashrrev_i32_e32 v9, 31, v8
	v_lshlrev_b64 v[8:9], 14, v[8:9]
	v_lshl_add_u64 v[8:9], v[4:5], 0, v[8:9]
	global_load_dword v231, v[8:9], off
	v_add_u32_e32 v8, 56, v6
	v_ashrrev_i32_e32 v9, 31, v8
	v_lshlrev_b64 v[8:9], 14, v[8:9]
	v_lshl_add_u64 v[8:9], v[4:5], 0, v[8:9]
	v_add_u32_e32 v6, 60, v6
	global_load_dword v232, v[8:9], off
	v_add_u32_e32 v8, 24, v2
	v_mov_b32_e32 v11, v8
	v_ashrrev_i32_e32 v7, 31, v6
	v_lshlrev_b64 v[6:7], 14, v[6:7]
	v_lshl_add_u64 v[4:5], v[4:5], 0, v[6:7]
	global_load_dword v233, v[4:5], off
	v_add_u32_e32 v6, 16, v2
	v_mov_b32_e32 v9, v6
	s_waitcnt vmcnt(15)
	ds_write_b32 v0, v218
	s_waitcnt vmcnt(14)
	ds_write_b32 v0, v219 offset:1040
	s_waitcnt vmcnt(13)
	ds_write_b32 v0, v220 offset:2080
	s_waitcnt vmcnt(12)
	ds_write_b32 v0, v221 offset:3120
	s_waitcnt vmcnt(11)
	ds_write_b32 v0, v222 offset:4160
	s_waitcnt vmcnt(10)
	ds_write_b32 v0, v223 offset:5200
	s_waitcnt vmcnt(9)
	ds_write_b32 v0, v224 offset:6240
	s_waitcnt vmcnt(8)
	ds_write_b32 v0, v225 offset:7280
	s_waitcnt vmcnt(7)
	ds_write_b32 v0, v226 offset:8320
	s_waitcnt vmcnt(6)
	ds_write_b32 v0, v227 offset:9360
	s_waitcnt vmcnt(5)
	ds_write_b32 v0, v228 offset:10400
	s_waitcnt vmcnt(4)
	ds_write_b32 v0, v229 offset:11440
	s_waitcnt vmcnt(3)
	ds_write_b32 v0, v230 offset:12480
	s_waitcnt vmcnt(2)
	ds_write_b32 v0, v231 offset:13520
	s_waitcnt vmcnt(1)
	ds_write_b32 v0, v232 offset:14560
	s_waitcnt vmcnt(0)
	ds_write_b32 v0, v233 offset:15600
	v_lshlrev_b32_e32 v0, 1, v3
	v_lshl_add_u64 v[4:5], s[6:7], 0, v[0:1]
	v_mov_b32_e32 v0, s88
	v_mad_u32_u24 v10, v3, s8, v0
	v_add_u32_e32 v0, 8, v2
	v_mov_b32_e32 v3, v2
	v_mov_b32_e32 v7, v0
	s_mov_b32 s6, 0
	s_waitcnt lgkmcnt(0)
	s_barrier

; DI void wtrans_tile(const float* __restrict__ src, int K, int N, u16* __restrict__ dst, int ldw, int tk, int tn,
;                     const float* __restrict__ kscale, char* lds) {
;     ...
;   const int tid = tid_, j = tid & 63, i0 = tid >> 6;
;   const int k0 = tk * 64, n0 = tn * 64;
;   __syncthreads();
; #pragma unroll
;   for (int q = 0; q < 16; ++q) {
;     int i = i0 + 4 * q;
;     float v = (n0 + j < N) ? src[(size_t)(k0 + i) * N + n0 + j] : 0.f;
;     if (kscale) v *= kscale[k0 + i];
;     t[i * 65 + j] = v;
;   }
.LBB0_497:
	s_andn2_b64 vcc, exec, s[0:1]
	s_movk_i32 s11, 0x900
	s_cbranch_vccnz .LBB0_500
	s_lshl_b32 s0, s3, 2
	s_and_b32 s0, s0, 0xfc0
	v_readlane_b32 s6, v252, 20
	s_add_i32 s6, s0, 0xfffff500
	s_lshl_b32 s0, s3, 6
	v_mov_b32_e32 v0, v248
	s_and_b32 s0, s0, 0x3c0
	s_lshl_b32 s1, s0, 2
	v_ashrrev_i32_e32 v2, 6, v0
	v_readlane_b32 s4, v251, 32
	v_and_b32_e32 v3, 63, v0
	s_add_u32 s4, s4, s1
	v_readlane_b32 s1, v251, 33
	v_add_u32_e32 v6, s6, v2
	s_addc_u32 s5, s1, 0
	v_lshlrev_b32_e32 v0, 2, v3
	v_ashrrev_i32_e32 v7, 31, v6
	v_lshl_add_u64 v[4:5], s[4:5], 0, v[0:1]
	v_lshlrev_b64 v[8:9], 12, v[6:7]
	v_lshl_add_u64 v[8:9], v[4:5], 0, v[8:9]
	s_barrier
	global_load_dword v218, v[8:9], off
	s_movk_i32 s8, 0x104
	v_mul_lo_u32 v8, v2, s8
	v_add3_u32 v0, s88, v8, v0
	v_add_u32_e32 v8, 4, v6
	v_ashrrev_i32_e32 v9, 31, v8
	v_lshlrev_b64 v[8:9], 12, v[8:9]
	v_lshl_add_u64 v[8:9], v[4:5], 0, v[8:9]
	v_readlane_b32 s7, v252, 21
	s_mov_b32 s4, 1
	s_mov_b32 s5, s7
	v_writelane_b32 v252, s4, 20
	s_lshl_b64 s[6:7], s[6:7], 1
	s_mov_b32 s1, 16
	v_writelane_b32 v252, s5, 21
	v_readlane_b32 s5, v251, 34
	s_add_u32 s6, s5, s6
	v_readlane_b32 s5, v251, 35
	s_addc_u32 s7, s5, s7
	s_mov_b32 s5, s0
	global_load_dword v219, v[8:9], off
	v_add_u32_e32 v8, 8, v6
	v_ashrrev_i32_e32 v9, 31, v8
	v_lshlrev_b64 v[8:9], 12, v[8:9]
	v_lshl_add_u64 v[8:9], v[4:5], 0, v[8:9]
	global_load_dword v220, v[8:9], off
	v_add_u32_e32 v8, 12, v6
	v_ashrrev_i32_e32 v9, 31, v8
	v_lshlrev_b64 v[8:9], 12, v[8:9]
	v_lshl_add_u64 v[8:9], v[4:5], 0, v[8:9]
	global_load_dword v221, v[8:9], off
	v_add_u32_e32 v8, 16, v6
	v_ashrrev_i32_e32 v9, 31, v8
	v_lshlrev_b64 v[8:9], 12, v[8:9]
	v_lshl_add_u64 v[8:9], v[4:5], 0, v[8:9]
	global_load_dword v222, v[8:9], off
	v_add_u32_e32 v8, 20, v6
	v_ashrrev_i32_e32 v9, 31, v8
	v_lshlrev_b64 v[8:9], 12, v[8:9]
	v_lshl_add_u64 v[8:9], v[4:5], 0, v[8:9]
	global_load_dword v223, v[8:9], off
	v_add_u32_e32 v8, 24, v6
	v_ashrrev_i32_e32 v9, 31, v8
	v_lshlrev_b64 v[8:9], 12, v[8:9]
	v_lshl_add_u64 v[8:9], v[4:5], 0, v[8:9]
	global_load_dword v224, v[8:9], off
	v_add_u32_e32 v8, 28, v6
	v_ashrrev_i32_e32 v9, 31, v8
	v_lshlrev_b64 v[8:9], 12, v[8:9]
	v_lshl_add_u64 v[8:9], v[4:5], 0, v[8:9]
	global_load_dword v225, v[8:9], off
	v_add_u32_e32 v8, 32, v6
	v_ashrrev_i32_e32 v9, 31, v8
	v_lshlrev_b64 v[8:9], 12, v[8:9]
	v_lshl_add_u64 v[8:9], v[4:5], 0, v[8:9]
	global_load_dword v226, v[8:9], off
	v_add_u32_e32 v8, 36, v6
	v_ashrrev_i32_e32 v9, 31, v8
	v_lshlrev_b64 v[8:9], 12, v[8:9]
	v_lshl_add_u64 v[8:9], v[4:5], 0, v[8:9]
	global_load_dword v227, v[8:9], off
	v_add_u32_e32 v8, 40, v6
	v_ashrrev_i32_e32 v9, 31, v8
	v_lshlrev_b64 v[8:9], 12, v[8:9]
	v_lshl_add_u64 v[8:9], v[4:5], 0, v[8:9]
	global_load_dword v228, v[8:9], off
	v_add_u32_e32 v8, 44, v6
	v_ashrrev_i32_e32 v9, 31, v8
	v_lshlrev_b64 v[8:9], 12, v[8:9]
	v_lshl_add_u64 v[8:9], v[4:5], 0, v[8:9]
	global_load_dword v229, v[8:9], off
	v_add_u32_e32 v8, 48, v6
	v_ashrrev_i32_e32 v9, 31, v8
	v_lshlrev_b64 v[8:9], 12, v[8:9]
	v_lshl_add_u64 v[8:9], v[4:5], 0, v[8:9]
	global_load_dword v230, v[8:9], off
	v_add_u32_e32 v8, 52, v6
	v_ashrrev_i32_e32 v9, 31, v8
	v_lshlrev_b64 v[8:9], 12, v[8:9]
	v_lshl_add_u64 v[8:9], v[4:5], 0, v[8:9]
	global_load_dword v231, v[8:9], off
	v_add_u32_e32 v8, 56, v6
	v_ashrrev_i32_e32 v9, 31, v8
	v_lshlrev_b64 v[8:9], 12, v[8:9]
	v_lshl_add_u64 v[8:9], v[4:5], 0, v[8:9]
	v_add_u32_e32 v6, 60, v6
	global_load_dword v232, v[8:9], off
	v_add_u32_e32 v8, 24, v2
	v_mov_b32_e32 v11, v8
	v_ashrrev_i32_e32 v7, 31, v6
	v_lshlrev_b64 v[6:7], 12, v[6:7]
	v_lshl_add_u64 v[4:5], v[4:5], 0, v[6:7]
	global_load_dword v233, v[4:5], off
	v_add_u32_e32 v6, 16, v2
	v_mov_b32_e32 v9, v6
	s_waitcnt vmcnt(15)
	ds_write_b32 v0, v218
	s_waitcnt vmcnt(14)
	ds_write_b32 v0, v219 offset:1040
	s_waitcnt vmcnt(13)
	ds_write_b32 v0, v220 offset:2080
	s_waitcnt vmcnt(12)
	ds_write_b32 v0, v221 offset:3120
	s_waitcnt vmcnt(11)
	ds_write_b32 v0, v222 offset:4160
	s_waitcnt vmcnt(10)
	ds_write_b32 v0, v223 offset:5200
	s_waitcnt vmcnt(9)
	ds_write_b32 v0, v224 offset:6240
	s_waitcnt vmcnt(8)
	ds_write_b32 v0, v225 offset:7280
	s_waitcnt vmcnt(7)
	ds_write_b32 v0, v226 offset:8320
	s_waitcnt vmcnt(6)
	ds_write_b32 v0, v227 offset:9360
	s_waitcnt vmcnt(5)
	ds_write_b32 v0, v228 offset:10400
	s_waitcnt vmcnt(4)
	ds_write_b32 v0, v229 offset:11440
	s_waitcnt vmcnt(3)
	ds_write_b32 v0, v230 offset:12480
	s_waitcnt vmcnt(2)
	ds_write_b32 v0, v231 offset:13520
	s_waitcnt vmcnt(1)
	ds_write_b32 v0, v232 offset:14560
	s_waitcnt vmcnt(0)
	ds_write_b32 v0, v233 offset:15600
	v_lshlrev_b32_e32 v0, 1, v3
	v_lshl_add_u64 v[4:5], s[6:7], 0, v[0:1]
	v_mov_b32_e32 v0, s88
	v_mad_u32_u24 v10, v3, s8, v0
	v_add_u32_e32 v0, 8, v2
	v_mov_b32_e32 v3, v2
	v_mov_b32_e32 v7, v0
	s_mov_b32 s6, 0
	s_waitcnt lgkmcnt(0)
	s_barrier

; DI void wtrans_tile(const float* __restrict__ src, int K, int N, u16* __restrict__ dst, int ldw, int tk, int tn,
;                     const float* __restrict__ kscale, char* lds) {
;     ...
;   const int tid = tid_, j = tid & 63, i0 = tid >> 6;
;   const int k0 = tk * 64, n0 = tn * 64;
;   __syncthreads();
; #pragma unroll
;   for (int q = 0; q < 16; ++q) {
;     int i = i0 + 4 * q;
;     float v = (n0 + j < N) ? src[(size_t)(k0 + i) * N + n0 + j] : 0.f;
;     if (kscale) v *= kscale[k0 + i];
;     t[i * 65 + j] = v;
;   }
; DI void wtile_deferred(const Params& p, int d, char* lds) {
;   if (d < 2304) wtile(p, 0, 704 + d, lds);
;   else wtile(p, 1, d - 2304, lds);
.LBB0_537:
	s_andn2_b64 vcc, exec, s[0:1]
	s_cbranch_vccnz .LBB0_550
	s_add_i32 s3, s2, 0x2c0
	s_cmpk_gt_u32 s2, 0xff
	s_mov_b64 s[0:1], -1
	s_cbranch_scc0 .LBB0_547
	s_cmpk_gt_u32 s2, 0x4ff
	s_cbranch_scc0 .LBB0_543
	s_lshl_b32 s0, s3, 2
	s_and_b32 s0, s0, 0x3fc0
	v_readlane_b32 s20, v252, 20
	s_add_i32 s20, s0, 0xffffe100
	s_lshl_b32 s0, s3, 6
	v_mov_b32_e32 v0, v248
	s_and_b32 s0, s0, 0x3c0
	v_readlane_b32 s4, v250, 16
	s_lshl_b32 s1, s0, 2
	v_ashrrev_i32_e32 v2, 6, v0
	v_readlane_b32 s16, v250, 28
	v_and_b32_e32 v3, 63, v0
	v_readlane_b32 s5, v250, 17
	v_readlane_b32 s17, v250, 29
	s_add_u32 s4, s16, s1
	v_add_u32_e32 v6, s20, v2
	s_addc_u32 s5, s17, 0
	v_lshlrev_b32_e32 v0, 2, v3
	v_ashrrev_i32_e32 v7, 31, v6
	v_lshl_add_u64 v[4:5], s[4:5], 0, v[0:1]
	v_lshlrev_b64 v[8:9], 12, v[6:7]
	v_lshl_add_u64 v[8:9], v[4:5], 0, v[8:9]
	s_barrier
	global_load_dword v218, v[8:9], off
	v_readlane_b32 s7, v250, 19
	s_movk_i32 s7, 0x104
	v_readlane_b32 s21, v252, 21
	v_mul_lo_u32 v8, v2, s7
	v_add3_u32 v0, s88, v8, v0
	v_add_u32_e32 v8, 4, v6
	v_ashrrev_i32_e32 v9, 31, v8
	v_lshlrev_b64 v[8:9], 12, v[8:9]
	v_lshl_add_u64 v[8:9], v[4:5], 0, v[8:9]
	s_mov_b32 s5, s21
	v_readlane_b32 s6, v250, 18
	v_writelane_b32 v252, s4, 20
	v_readlane_b32 s6, v251, 40
	v_readlane_b32 s10, v250, 22
	v_writelane_b32 v252, s5, 21
	s_lshl_b64 s[4:5], s[20:21], 1
	s_add_u32 s4, s6, s4
	v_readlane_b32 s6, v251, 41
	s_addc_u32 s5, s6, s5
	s_mov_b32 s1, 16
	s_mov_b32 s2, 1
	s_movk_i32 s10, 0x2100
	v_readlane_b32 s8, v250, 20
	v_readlane_b32 s9, v250, 21
	v_readlane_b32 s11, v250, 23
	v_readlane_b32 s12, v250, 24
	v_readlane_b32 s13, v250, 25
	v_readlane_b32 s14, v250, 26
	v_readlane_b32 s15, v250, 27
	v_readlane_b32 s18, v250, 30
	v_readlane_b32 s19, v250, 31
	global_load_dword v219, v[8:9], off
	v_add_u32_e32 v8, 8, v6
	v_ashrrev_i32_e32 v9, 31, v8
	v_lshlrev_b64 v[8:9], 12, v[8:9]
	v_lshl_add_u64 v[8:9], v[4:5], 0, v[8:9]
	global_load_dword v220, v[8:9], off
	v_add_u32_e32 v8, 12, v6
	v_ashrrev_i32_e32 v9, 31, v8
	v_lshlrev_b64 v[8:9], 12, v[8:9]
	v_lshl_add_u64 v[8:9], v[4:5], 0, v[8:9]
	global_load_dword v221, v[8:9], off
	v_add_u32_e32 v8, 16, v6
	v_ashrrev_i32_e32 v9, 31, v8
	v_lshlrev_b64 v[8:9], 12, v[8:9]
	v_lshl_add_u64 v[8:9], v[4:5], 0, v[8:9]
	global_load_dword v222, v[8:9], off
	v_add_u32_e32 v8, 20, v6
	v_ashrrev_i32_e32 v9, 31, v8
	v_lshlrev_b64 v[8:9], 12, v[8:9]
	v_lshl_add_u64 v[8:9], v[4:5], 0, v[8:9]
	global_load_dword v223, v[8:9], off
	v_add_u32_e32 v8, 24, v6
	v_ashrrev_i32_e32 v9, 31, v8
	v_lshlrev_b64 v[8:9], 12, v[8:9]
	v_lshl_add_u64 v[8:9], v[4:5], 0, v[8:9]
	global_load_dword v224, v[8:9], off
	v_add_u32_e32 v8, 28, v6
	v_ashrrev_i32_e32 v9, 31, v8
	v_lshlrev_b64 v[8:9], 12, v[8:9]
	v_lshl_add_u64 v[8:9], v[4:5], 0, v[8:9]
	global_load_dword v225, v[8:9], off
	v_add_u32_e32 v8, 32, v6
	v_ashrrev_i32_e32 v9, 31, v8
	v_lshlrev_b64 v[8:9], 12, v[8:9]
	v_lshl_add_u64 v[8:9], v[4:5], 0, v[8:9]
	global_load_dword v226, v[8:9], off
	v_add_u32_e32 v8, 36, v6
	v_ashrrev_i32_e32 v9, 31, v8
	v_lshlrev_b64 v[8:9], 12, v[8:9]
	v_lshl_add_u64 v[8:9], v[4:5], 0, v[8:9]
	global_load_dword v227, v[8:9], off
	v_add_u32_e32 v8, 40, v6
	v_ashrrev_i32_e32 v9, 31, v8
	v_lshlrev_b64 v[8:9], 12, v[8:9]
	v_lshl_add_u64 v[8:9], v[4:5], 0, v[8:9]
	global_load_dword v228, v[8:9], off
	v_add_u32_e32 v8, 44, v6
	v_ashrrev_i32_e32 v9, 31, v8
	v_lshlrev_b64 v[8:9], 12, v[8:9]
	v_lshl_add_u64 v[8:9], v[4:5], 0, v[8:9]
	global_load_dword v229, v[8:9], off
	v_add_u32_e32 v8, 48, v6
	v_ashrrev_i32_e32 v9, 31, v8
	v_lshlrev_b64 v[8:9], 12, v[8:9]
	v_lshl_add_u64 v[8:9], v[4:5], 0, v[8:9]
	global_load_dword v230, v[8:9], off
	v_add_u32_e32 v8, 52, v6
	v_ashrrev_i32_e32 v9, 31, v8
	v_lshlrev_b64 v[8:9], 12, v[8:9]
	v_lshl_add_u64 v[8:9], v[4:5], 0, v[8:9]
	global_load_dword v231, v[8:9], off
	v_add_u32_e32 v8, 56, v6
	v_ashrrev_i32_e32 v9, 31, v8
	v_lshlrev_b64 v[8:9], 12, v[8:9]
	v_lshl_add_u64 v[8:9], v[4:5], 0, v[8:9]
	v_add_u32_e32 v6, 60, v6
	global_load_dword v232, v[8:9], off
	v_add_u32_e32 v8, 24, v2
	v_mov_b32_e32 v11, v8
	v_ashrrev_i32_e32 v7, 31, v6
	v_lshlrev_b64 v[6:7], 12, v[6:7]
	v_lshl_add_u64 v[4:5], v[4:5], 0, v[6:7]
	global_load_dword v233, v[4:5], off
	v_add_u32_e32 v6, 16, v2
	v_mov_b32_e32 v9, v6
	s_waitcnt vmcnt(15)
	ds_write_b32 v0, v218
	s_waitcnt vmcnt(14)
	ds_write_b32 v0, v219 offset:1040
	s_waitcnt vmcnt(13)
	ds_write_b32 v0, v220 offset:2080
	s_waitcnt vmcnt(12)
	ds_write_b32 v0, v221 offset:3120
	s_waitcnt vmcnt(11)
	ds_write_b32 v0, v222 offset:4160
	s_waitcnt vmcnt(10)
	ds_write_b32 v0, v223 offset:5200
	s_waitcnt vmcnt(9)
	ds_write_b32 v0, v224 offset:6240
	s_waitcnt vmcnt(8)
	ds_write_b32 v0, v225 offset:7280
	s_waitcnt vmcnt(7)
	ds_write_b32 v0, v226 offset:8320
	s_waitcnt vmcnt(6)
	ds_write_b32 v0, v227 offset:9360
	s_waitcnt vmcnt(5)
	ds_write_b32 v0, v228 offset:10400
	s_waitcnt vmcnt(4)
	ds_write_b32 v0, v229 offset:11440
	s_waitcnt vmcnt(3)
	ds_write_b32 v0, v230 offset:12480
	s_waitcnt vmcnt(2)
	ds_write_b32 v0, v231 offset:13520
	s_waitcnt vmcnt(1)
	ds_write_b32 v0, v232 offset:14560
	s_waitcnt vmcnt(0)
	ds_write_b32 v0, v233 offset:15600
	v_lshlrev_b32_e32 v0, 1, v3
	v_lshl_add_u64 v[4:5], s[4:5], 0, v[0:1]
	v_mov_b32_e32 v0, s88
	v_mad_u32_u24 v10, v3, s7, v0
	v_add_u32_e32 v0, 8, v2
	v_mov_b32_e32 v3, v2
	s_mov_b32 s4, s0
	v_mov_b32_e32 v7, v0
	s_mov_b32 s5, 0
	s_waitcnt lgkmcnt(0)
	s_barrier

; DI void wtrans_tile(const float* __restrict__ src, int K, int N, u16* __restrict__ dst, int ldw, int tk, int tn,
;                     const float* __restrict__ kscale, char* lds) {
;     ...
;   const int tid = tid_, j = tid & 63, i0 = tid >> 6;
;   const int k0 = tk * 64, n0 = tn * 64;
;   __syncthreads();
; #pragma unroll
;   for (int q = 0; q < 16; ++q) {
;     int i = i0 + 4 * q;
;     float v = (n0 + j < N) ? src[(size_t)(k0 + i) * N + n0 + j] : 0.f;
;     if (kscale) v *= kscale[k0 + i];
;     t[i * 65 + j] = v;
;   }
.LBB0_543:
	s_and_b64 vcc, exec, s[0:1]
	s_movk_i32 s20, 0x900
	s_cbranch_vccz .LBB0_546
	s_and_b32 s0, s3, 0x7c0
	v_readlane_b32 s22, v252, 20
	s_add_i32 s22, s0, 0xfffffc40
	s_lshl_b32 s0, s3, 6
	v_mov_b32_e32 v0, v248
	s_and_b32 s0, s0, 0xfc0
	v_readlane_b32 s4, v250, 16
	s_lshl_b32 s1, s0, 2
	v_ashrrev_i32_e32 v2, 6, v0
	v_readlane_b32 s14, v250, 26
	v_and_b32_e32 v3, 63, v0
	v_readlane_b32 s5, v250, 17
	v_readlane_b32 s15, v250, 27
	s_add_u32 s4, s14, s1
	v_add_u32_e32 v6, s22, v2
	s_addc_u32 s5, s15, 0
	v_lshlrev_b32_e32 v0, 2, v3
	v_ashrrev_i32_e32 v7, 31, v6
	v_lshl_add_u64 v[4:5], s[4:5], 0, v[0:1]
	v_lshlrev_b64 v[8:9], 14, v[6:7]
	v_lshl_add_u64 v[8:9], v[4:5], 0, v[8:9]
	s_barrier
	global_load_dword v218, v[8:9], off
	v_readlane_b32 s7, v250, 19
	s_movk_i32 s7, 0x104
	v_readlane_b32 s23, v252, 21
	v_mul_lo_u32 v8, v2, s7
	v_add3_u32 v0, s88, v8, v0
	v_add_u32_e32 v8, 4, v6
	v_ashrrev_i32_e32 v9, 31, v8
	v_lshlrev_b64 v[8:9], 14, v[8:9]
	v_lshl_add_u64 v[8:9], v[4:5], 0, v[8:9]
	s_mov_b32 s5, s23
	v_readlane_b32 s6, v250, 18
	v_writelane_b32 v252, s4, 20
	v_readlane_b32 s6, v251, 42
	s_mov_b32 s1, 16
	v_writelane_b32 v252, s5, 21
	s_lshl_b64 s[4:5], s[22:23], 1
	s_add_u32 s4, s6, s4
	v_readlane_b32 s6, v251, 43
	s_addc_u32 s5, s6, s5
	s_mov_b32 s2, 1
	v_readlane_b32 s8, v250, 20
	v_readlane_b32 s9, v250, 21
	v_readlane_b32 s10, v250, 22
	v_readlane_b32 s11, v250, 23
	v_readlane_b32 s12, v250, 24
	v_readlane_b32 s13, v250, 25
	v_readlane_b32 s16, v250, 28
	v_readlane_b32 s17, v250, 29
	v_readlane_b32 s18, v250, 30
	v_readlane_b32 s19, v250, 31
	global_load_dword v219, v[8:9], off
	v_add_u32_e32 v8, 8, v6
	v_ashrrev_i32_e32 v9, 31, v8
	v_lshlrev_b64 v[8:9], 14, v[8:9]
	v_lshl_add_u64 v[8:9], v[4:5], 0, v[8:9]
	global_load_dword v220, v[8:9], off
	v_add_u32_e32 v8, 12, v6
	v_ashrrev_i32_e32 v9, 31, v8
	v_lshlrev_b64 v[8:9], 14, v[8:9]
	v_lshl_add_u64 v[8:9], v[4:5], 0, v[8:9]
	global_load_dword v221, v[8:9], off
	v_add_u32_e32 v8, 16, v6
	v_ashrrev_i32_e32 v9, 31, v8
	v_lshlrev_b64 v[8:9], 14, v[8:9]
	v_lshl_add_u64 v[8:9], v[4:5], 0, v[8:9]
	global_load_dword v222, v[8:9], off
	v_add_u32_e32 v8, 20, v6
	v_ashrrev_i32_e32 v9, 31, v8
	v_lshlrev_b64 v[8:9], 14, v[8:9]
	v_lshl_add_u64 v[8:9], v[4:5], 0, v[8:9]
	global_load_dword v223, v[8:9], off
	v_add_u32_e32 v8, 24, v6
	v_ashrrev_i32_e32 v9, 31, v8
	v_lshlrev_b64 v[8:9], 14, v[8:9]
	v_lshl_add_u64 v[8:9], v[4:5], 0, v[8:9]
	global_load_dword v224, v[8:9], off
	v_add_u32_e32 v8, 28, v6
	v_ashrrev_i32_e32 v9, 31, v8
	v_lshlrev_b64 v[8:9], 14, v[8:9]
	v_lshl_add_u64 v[8:9], v[4:5], 0, v[8:9]
	global_load_dword v225, v[8:9], off
	v_add_u32_e32 v8, 32, v6
	v_ashrrev_i32_e32 v9, 31, v8
	v_lshlrev_b64 v[8:9], 14, v[8:9]
	v_lshl_add_u64 v[8:9], v[4:5], 0, v[8:9]
	global_load_dword v226, v[8:9], off
	v_add_u32_e32 v8, 36, v6
	v_ashrrev_i32_e32 v9, 31, v8
	v_lshlrev_b64 v[8:9], 14, v[8:9]
	v_lshl_add_u64 v[8:9], v[4:5], 0, v[8:9]
	global_load_dword v227, v[8:9], off
	v_add_u32_e32 v8, 40, v6
	v_ashrrev_i32_e32 v9, 31, v8
	v_lshlrev_b64 v[8:9], 14, v[8:9]
	v_lshl_add_u64 v[8:9], v[4:5], 0, v[8:9]
	global_load_dword v228, v[8:9], off
	v_add_u32_e32 v8, 44, v6
	v_ashrrev_i32_e32 v9, 31, v8
	v_lshlrev_b64 v[8:9], 14, v[8:9]
	v_lshl_add_u64 v[8:9], v[4:5], 0, v[8:9]
	global_load_dword v229, v[8:9], off
	v_add_u32_e32 v8, 48, v6
	v_ashrrev_i32_e32 v9, 31, v8
	v_lshlrev_b64 v[8:9], 14, v[8:9]
	v_lshl_add_u64 v[8:9], v[4:5], 0, v[8:9]
	global_load_dword v230, v[8:9], off
	v_add_u32_e32 v8, 52, v6
	v_ashrrev_i32_e32 v9, 31, v8
	v_lshlrev_b64 v[8:9], 14, v[8:9]
	v_lshl_add_u64 v[8:9], v[4:5], 0, v[8:9]
	global_load_dword v231, v[8:9], off
	v_add_u32_e32 v8, 56, v6
	v_ashrrev_i32_e32 v9, 31, v8
	v_lshlrev_b64 v[8:9], 14, v[8:9]
	v_lshl_add_u64 v[8:9], v[4:5], 0, v[8:9]
	v_add_u32_e32 v6, 60, v6
	global_load_dword v232, v[8:9], off
	v_add_u32_e32 v8, 24, v2
	v_mov_b32_e32 v11, v8
	v_ashrrev_i32_e32 v7, 31, v6
	v_lshlrev_b64 v[6:7], 14, v[6:7]
	v_lshl_add_u64 v[4:5], v[4:5], 0, v[6:7]
	global_load_dword v233, v[4:5], off
	v_add_u32_e32 v6, 16, v2
	v_mov_b32_e32 v9, v6
	s_waitcnt vmcnt(15)
	ds_write_b32 v0, v218
	s_waitcnt vmcnt(14)
	ds_write_b32 v0, v219 offset:1040
	s_waitcnt vmcnt(13)
	ds_write_b32 v0, v220 offset:2080
	s_waitcnt vmcnt(12)
	ds_write_b32 v0, v221 offset:3120
	s_waitcnt vmcnt(11)
	ds_write_b32 v0, v222 offset:4160
	s_waitcnt vmcnt(10)
	ds_write_b32 v0, v223 offset:5200
	s_waitcnt vmcnt(9)
	ds_write_b32 v0, v224 offset:6240
	s_waitcnt vmcnt(8)
	ds_write_b32 v0, v225 offset:7280
	s_waitcnt vmcnt(7)
	ds_write_b32 v0, v226 offset:8320
	s_waitcnt vmcnt(6)
	ds_write_b32 v0, v227 offset:9360
	s_waitcnt vmcnt(5)
	ds_write_b32 v0, v228 offset:10400
	s_waitcnt vmcnt(4)
	ds_write_b32 v0, v229 offset:11440
	s_waitcnt vmcnt(3)
	ds_write_b32 v0, v230 offset:12480
	s_waitcnt vmcnt(2)
	ds_write_b32 v0, v231 offset:13520
	s_waitcnt vmcnt(1)
	ds_write_b32 v0, v232 offset:14560
	s_waitcnt vmcnt(0)
	ds_write_b32 v0, v233 offset:15600
	v_lshlrev_b32_e32 v0, 1, v3
	v_lshl_add_u64 v[4:5], s[4:5], 0, v[0:1]
	v_mov_b32_e32 v0, s88
	v_mad_u32_u24 v10, v3, s7, v0
	v_add_u32_e32 v0, 8, v2
	v_mov_b32_e32 v3, v2
	s_mov_b32 s4, s0
	v_mov_b32_e32 v7, v0
	s_mov_b32 s5, 0
	s_waitcnt lgkmcnt(0)
	s_barrier

; DI void wtrans_tile(const float* __restrict__ src, int K, int N, u16* __restrict__ dst, int ldw, int tk, int tn,
;                     const float* __restrict__ kscale, char* lds) {
;     ...
;   const int tid = tid_, j = tid & 63, i0 = tid >> 6;
;   const int k0 = tk * 64, n0 = tn * 64;
;   __syncthreads();
; #pragma unroll
;   for (int q = 0; q < 16; ++q) {
;     int i = i0 + 4 * q;
;     float v = (n0 + j < N) ? src[(size_t)(k0 + i) * N + n0 + j] : 0.f;
;     if (kscale) v *= kscale[k0 + i];
;     t[i * 65 + j] = v;
;   }
.LBB0_547:
	s_andn2_b64 vcc, exec, s[0:1]
	s_movk_i32 s20, 0x900
	s_cbranch_vccnz .LBB0_550
	s_lshl_b32 s0, s3, 2
	s_and_b32 s0, s0, 0xfc0
	v_readlane_b32 s22, v252, 20
	s_add_i32 s22, s0, 0xfffff500
	s_lshl_b32 s0, s3, 6
	v_mov_b32_e32 v0, v248
	s_and_b32 s0, s0, 0x3c0
	v_readlane_b32 s4, v250, 16
	s_lshl_b32 s1, s0, 2
	v_ashrrev_i32_e32 v2, 6, v0
	v_readlane_b32 s8, v250, 20
	v_and_b32_e32 v3, 63, v0
	v_readlane_b32 s9, v250, 21
	s_add_u32 s2, s8, s1
	v_add_u32_e32 v6, s22, v2
	s_addc_u32 s3, s9, 0
	v_lshlrev_b32_e32 v0, 2, v3
	v_ashrrev_i32_e32 v7, 31, v6
	v_lshl_add_u64 v[4:5], s[2:3], 0, v[0:1]
	v_lshlrev_b64 v[8:9], 12, v[6:7]
	v_lshl_add_u64 v[8:9], v[4:5], 0, v[8:9]
	s_barrier
	global_load_dword v218, v[8:9], off
	v_readlane_b32 s6, v250, 18
	s_movk_i32 s6, 0x104
	v_readlane_b32 s23, v252, 21
	v_mul_lo_u32 v8, v2, s6
	v_add3_u32 v0, s88, v8, v0
	v_add_u32_e32 v8, 4, v6
	v_ashrrev_i32_e32 v9, 31, v8
	v_lshlrev_b64 v[8:9], 12, v[8:9]
	v_lshl_add_u64 v[8:9], v[4:5], 0, v[8:9]
	s_mov_b32 s2, 1
	s_mov_b32 s3, s23
	v_readlane_b32 s5, v250, 17
	v_writelane_b32 v252, s2, 20
	s_lshl_b64 s[4:5], s[22:23], 1
	s_mov_b32 s1, 16
	v_writelane_b32 v252, s3, 21
	v_readlane_b32 s3, v251, 44
	s_add_u32 s4, s3, s4
	v_readlane_b32 s3, v251, 45
	s_addc_u32 s5, s3, s5
	s_mov_b32 s3, s0
	v_readlane_b32 s7, v250, 19
	v_readlane_b32 s10, v250, 22
	v_readlane_b32 s11, v250, 23
	v_readlane_b32 s12, v250, 24
	v_readlane_b32 s13, v250, 25
	v_readlane_b32 s14, v250, 26
	v_readlane_b32 s15, v250, 27
	v_readlane_b32 s16, v250, 28
	v_readlane_b32 s17, v250, 29
	v_readlane_b32 s18, v250, 30
	v_readlane_b32 s19, v250, 31
	global_load_dword v219, v[8:9], off
	v_add_u32_e32 v8, 8, v6
	v_ashrrev_i32_e32 v9, 31, v8
	v_lshlrev_b64 v[8:9], 12, v[8:9]
	v_lshl_add_u64 v[8:9], v[4:5], 0, v[8:9]
	global_load_dword v220, v[8:9], off
	v_add_u32_e32 v8, 12, v6
	v_ashrrev_i32_e32 v9, 31, v8
	v_lshlrev_b64 v[8:9], 12, v[8:9]
	v_lshl_add_u64 v[8:9], v[4:5], 0, v[8:9]
	global_load_dword v221, v[8:9], off
	v_add_u32_e32 v8, 16, v6
	v_ashrrev_i32_e32 v9, 31, v8
	v_lshlrev_b64 v[8:9], 12, v[8:9]
	v_lshl_add_u64 v[8:9], v[4:5], 0, v[8:9]
	global_load_dword v222, v[8:9], off
	v_add_u32_e32 v8, 20, v6
	v_ashrrev_i32_e32 v9, 31, v8
	v_lshlrev_b64 v[8:9], 12, v[8:9]
	v_lshl_add_u64 v[8:9], v[4:5], 0, v[8:9]
	global_load_dword v223, v[8:9], off
	v_add_u32_e32 v8, 24, v6
	v_ashrrev_i32_e32 v9, 31, v8
	v_lshlrev_b64 v[8:9], 12, v[8:9]
	v_lshl_add_u64 v[8:9], v[4:5], 0, v[8:9]
	global_load_dword v224, v[8:9], off
	v_add_u32_e32 v8, 28, v6
	v_ashrrev_i32_e32 v9, 31, v8
	v_lshlrev_b64 v[8:9], 12, v[8:9]
	v_lshl_add_u64 v[8:9], v[4:5], 0, v[8:9]
	global_load_dword v225, v[8:9], off
	v_add_u32_e32 v8, 32, v6
	v_ashrrev_i32_e32 v9, 31, v8
	v_lshlrev_b64 v[8:9], 12, v[8:9]
	v_lshl_add_u64 v[8:9], v[4:5], 0, v[8:9]
	global_load_dword v226, v[8:9], off
	v_add_u32_e32 v8, 36, v6
	v_ashrrev_i32_e32 v9, 31, v8
	v_lshlrev_b64 v[8:9], 12, v[8:9]
	v_lshl_add_u64 v[8:9], v[4:5], 0, v[8:9]
	global_load_dword v227, v[8:9], off
	v_add_u32_e32 v8, 40, v6
	v_ashrrev_i32_e32 v9, 31, v8
	v_lshlrev_b64 v[8:9], 12, v[8:9]
	v_lshl_add_u64 v[8:9], v[4:5], 0, v[8:9]
	global_load_dword v228, v[8:9], off
	v_add_u32_e32 v8, 44, v6
	v_ashrrev_i32_e32 v9, 31, v8
	v_lshlrev_b64 v[8:9], 12, v[8:9]
	v_lshl_add_u64 v[8:9], v[4:5], 0, v[8:9]
	global_load_dword v229, v[8:9], off
	v_add_u32_e32 v8, 48, v6
	v_ashrrev_i32_e32 v9, 31, v8
	v_lshlrev_b64 v[8:9], 12, v[8:9]
	v_lshl_add_u64 v[8:9], v[4:5], 0, v[8:9]
	global_load_dword v230, v[8:9], off
	v_add_u32_e32 v8, 52, v6
	v_ashrrev_i32_e32 v9, 31, v8
	v_lshlrev_b64 v[8:9], 12, v[8:9]
	v_lshl_add_u64 v[8:9], v[4:5], 0, v[8:9]
	global_load_dword v231, v[8:9], off
	v_add_u32_e32 v8, 56, v6
	v_ashrrev_i32_e32 v9, 31, v8
	v_lshlrev_b64 v[8:9], 12, v[8:9]
	v_lshl_add_u64 v[8:9], v[4:5], 0, v[8:9]
	v_add_u32_e32 v6, 60, v6
	global_load_dword v232, v[8:9], off
	v_add_u32_e32 v8, 24, v2
	v_mov_b32_e32 v11, v8
	v_ashrrev_i32_e32 v7, 31, v6
	v_lshlrev_b64 v[6:7], 12, v[6:7]
	v_lshl_add_u64 v[4:5], v[4:5], 0, v[6:7]
	global_load_dword v233, v[4:5], off
	v_add_u32_e32 v6, 16, v2
	v_mov_b32_e32 v9, v6
	s_waitcnt vmcnt(15)
	ds_write_b32 v0, v218
	s_waitcnt vmcnt(14)
	ds_write_b32 v0, v219 offset:1040
	s_waitcnt vmcnt(13)
	ds_write_b32 v0, v220 offset:2080
	s_waitcnt vmcnt(12)
	ds_write_b32 v0, v221 offset:3120
	s_waitcnt vmcnt(11)
	ds_write_b32 v0, v222 offset:4160
	s_waitcnt vmcnt(10)
	ds_write_b32 v0, v223 offset:5200
	s_waitcnt vmcnt(9)
	ds_write_b32 v0, v224 offset:6240
	s_waitcnt vmcnt(8)
	ds_write_b32 v0, v225 offset:7280
	s_waitcnt vmcnt(7)
	ds_write_b32 v0, v226 offset:8320
	s_waitcnt vmcnt(6)
	ds_write_b32 v0, v227 offset:9360
	s_waitcnt vmcnt(5)
	ds_write_b32 v0, v228 offset:10400
	s_waitcnt vmcnt(4)
	ds_write_b32 v0, v229 offset:11440
	s_waitcnt vmcnt(3)
	ds_write_b32 v0, v230 offset:12480
	s_waitcnt vmcnt(2)
	ds_write_b32 v0, v231 offset:13520
	s_waitcnt vmcnt(1)
	ds_write_b32 v0, v232 offset:14560
	s_waitcnt vmcnt(0)
	ds_write_b32 v0, v233 offset:15600
	v_lshlrev_b32_e32 v0, 1, v3
	v_lshl_add_u64 v[4:5], s[4:5], 0, v[0:1]
	v_mov_b32_e32 v0, s88
	v_mad_u32_u24 v10, v3, s6, v0
	v_add_u32_e32 v0, 8, v2
	v_mov_b32_e32 v3, v2
	v_mov_b32_e32 v7, v0
	s_mov_b32 s4, 0
	s_waitcnt lgkmcnt(0)
	s_barrier

; DI int crow(int reg, int h) { return (reg & 3) + 8 * (reg >> 2) + 4 * h; }
; DI void dn_chain(const Params& p, int chain, char* lds) {
;     ...
;     {
;       f32x16 kk = mm64<4>(kA, LS, kA, LS, wm, wn, r, h);
;       const int s = wn * 32 + r;
;       const float gs = gc[s];
; #pragma unroll
;       for (int g = 0; g < 16; ++g) {
;         int c = wm * 32 + crow(g, h);
;         float v = (s < c) ? bt[c] * kk[g] * __expf(gc[c] - gs) : 0.f;
;         kk[g] = v;
;         T[g] = (c == s) ? 1.f : (((c >> 1) == (s >> 1)) ? -v : 0.f);
;       }
;       st_transp(R1, LS, kk, wm, wn, r, h);
;       st_transp(R2, LS, T, wm, wn, r, h);
;     }
;     __syncthreads();
;     for (int k = 1; k < 6; ++k) {
;       f32x16 M = mm64t<4>(R1, LS, R2, LS, wm, wn, r, h, lane);
;       st_transp(R4, LS, M, wm, wn, r, h);
;       __syncthreads();
;       f32x16 X = mm64t<4>(R2, LS, R4, LS, wm, wn, r, h, lane);
.LBB0_693:
	s_or_b64 exec, exec, s[4:5]
	v_readlane_b32 s4, v252, 57
	v_cndmask_b32_e64 v16, 0, -v43, s[20:21]
	v_readlane_b32 s5, v252, 58
	v_cvt_pk_bf16_f32 v17, v42, v4
	v_add_u32_e32 v140, 0x4800, v115
	v_cndmask_b32_e64 v48, v16, 1.0, s[4:5]
	v_readlane_b32 s4, v252, 59
	v_cndmask_b32_e64 v16, 0, -v2, s[20:21]
	v_readlane_b32 s5, v252, 60
	v_add_u32_e32 v141, 0xb000, v118
	s_nop 0
	v_cndmask_b32_e64 v49, v16, 1.0, s[4:5]
	v_readlane_b32 s4, v253, 53
	v_readlane_b32 s5, v253, 54
	s_nop 1
	v_cndmask_b32_e64 v16, 0, -v42, s[4:5]
	v_readlane_b32 s4, v252, 63
	v_readlane_b32 s5, v253, 0
	v_add_u32_e32 v42, 0x6800, v115
	s_nop 0
	v_cndmask_b32_e64 v100, v16, 1.0, s[4:5]
	v_readlane_b32 s4, v253, 57
	v_readlane_b32 s5, v253, 58
	s_nop 1
	v_cndmask_b32_e64 v16, 0, -v4, s[4:5]
	v_readlane_b32 s4, v253, 3
	v_readlane_b32 s5, v253, 4
	v_cvt_pk_bf16_f32 v4, v11, v14
	s_nop 0
	v_cndmask_b32_e64 v101, v16, 1.0, s[4:5]
	v_readlane_b32 s4, v253, 61
	v_readlane_b32 s5, v253, 62
	s_nop 1
	v_cndmask_b32_e64 v16, 0, -v3, s[4:5]
	v_readlane_b32 s4, v253, 7
	v_readlane_b32 s5, v253, 8
	s_nop 1
	v_cndmask_b32_e64 v102, v16, 1.0, s[4:5]
	v_readlane_b32 s4, v254, 1
	v_readlane_b32 s5, v254, 2
	s_nop 1
	v_cndmask_b32_e64 v16, 0, -v6, s[4:5]
	v_readlane_b32 s4, v253, 11
	v_readlane_b32 s5, v253, 12
	s_nop 1
	v_cndmask_b32_e64 v103, v16, 1.0, s[4:5]
	v_readlane_b32 s4, v254, 5
	v_readlane_b32 s5, v254, 6
	s_nop 1
	v_cndmask_b32_e64 v16, 0, -v5, s[4:5]
	v_readlane_b32 s4, v253, 15
	v_readlane_b32 s5, v253, 16
	s_nop 1
	v_cndmask_b32_e64 v142, v16, 1.0, s[4:5]
	v_readlane_b32 s4, v254, 9
	v_readlane_b32 s5, v254, 10
	s_nop 1
	v_cndmask_b32_e64 v16, 0, -v8, s[4:5]
	v_readlane_b32 s4, v253, 19
	v_readlane_b32 s5, v253, 20
	s_nop 1
	v_cndmask_b32_e64 v143, v16, 1.0, s[4:5]
	v_readlane_b32 s4, v254, 13
	v_readlane_b32 s5, v254, 14
	s_nop 1
	v_cndmask_b32_e64 v16, 0, -v7, s[4:5]
	v_readlane_b32 s4, v253, 23
	v_readlane_b32 s5, v253, 24
	s_nop 1
	v_cndmask_b32_e64 v144, v16, 1.0, s[4:5]
	v_readlane_b32 s4, v254, 17
	v_readlane_b32 s5, v254, 18
	s_nop 1
	v_cndmask_b32_e64 v16, 0, -v10, s[4:5]
	v_readlane_b32 s4, v253, 27
	v_readlane_b32 s5, v253, 28
	s_nop 1
	v_cndmask_b32_e64 v145, v16, 1.0, s[4:5]
	v_readlane_b32 s4, v254, 21
	v_readlane_b32 s5, v254, 22
	s_nop 1
	v_cndmask_b32_e64 v16, 0, -v9, s[4:5]
	v_readlane_b32 s4, v253, 31
	v_readlane_b32 s5, v253, 32
	s_nop 1
	v_cndmask_b32_e64 v146, v16, 1.0, s[4:5]
	v_readlane_b32 s4, v254, 25
	v_readlane_b32 s5, v254, 26
	s_nop 1
	v_cndmask_b32_e64 v16, 0, -v12, s[4:5]
	v_readlane_b32 s4, v253, 35
	v_readlane_b32 s5, v253, 36
	s_nop 1
	v_cndmask_b32_e64 v147, v16, 1.0, s[4:5]
	v_readlane_b32 s4, v254, 29
	v_readlane_b32 s5, v254, 30
	s_nop 1
	v_cndmask_b32_e64 v16, 0, -v11, s[4:5]
	v_readlane_b32 s4, v253, 39
	v_readlane_b32 s5, v253, 40
	s_nop 1
	v_cndmask_b32_e64 v148, v16, 1.0, s[4:5]
	v_readlane_b32 s4, v254, 33
	v_readlane_b32 s5, v254, 34
	s_nop 1
	v_cndmask_b32_e64 v16, 0, -v14, s[4:5]
	v_readlane_b32 s4, v253, 43
	v_readlane_b32 s5, v253, 44
	s_nop 1
	v_cndmask_b32_e64 v149, v16, 1.0, s[4:5]
	v_readlane_b32 s4, v254, 37
	v_readlane_b32 s5, v254, 38
	s_nop 1
	v_cndmask_b32_e64 v16, 0, -v13, s[4:5]
	v_readlane_b32 s4, v253, 47
	v_readlane_b32 s5, v253, 48
	s_nop 1
	v_cndmask_b32_e64 v150, v16, 1.0, s[4:5]
	v_readlane_b32 s4, v254, 41
	v_readlane_b32 s5, v254, 42
	s_nop 1
	v_cndmask_b32_e64 v16, 0, -v15, s[4:5]
	v_readlane_b32 s4, v253, 51
	v_readlane_b32 s5, v253, 52
	s_nop 1
	v_cndmask_b32_e64 v151, v16, 1.0, s[4:5]
	v_cvt_pk_bf16_f32 v16, v43, v2
	v_cvt_pk_bf16_f32 v2, v3, v6
	v_cvt_pk_bf16_f32 v3, v5, v8
	ds_write2_b64 v140, v[16:17], v[2:3] offset1:2
	v_cvt_pk_bf16_f32 v2, v7, v10
	v_cvt_pk_bf16_f32 v3, v9, v12
	v_cvt_pk_bf16_f32 v5, v13, v15
	ds_write2_b64 v140, v[2:3], v[4:5] offset0:4 offset1:6
	v_cvt_pk_bf16_f32 v2, v48, v49
	v_cvt_pk_bf16_f32 v3, v100, v101
	v_cvt_pk_bf16_f32 v4, v102, v103
	v_cvt_pk_bf16_f32 v5, v142, v143
	ds_write2_b64 v42, v[2:3], v[4:5] offset0:128 offset1:130
	v_cvt_pk_bf16_f32 v2, v144, v145
	v_cvt_pk_bf16_f32 v3, v146, v147
	v_cvt_pk_bf16_f32 v4, v148, v149
	v_cvt_pk_bf16_f32 v5, v150, v151
	ds_write2_b64 v42, v[2:3], v[4:5] offset0:132 offset1:134
	s_waitcnt lgkmcnt(0)
	s_barrier
	ds_read_b64_tr_b16 v[2:3], v117 offset:18432
	ds_read_b64_tr_b16 v[4:5], v117 offset:19008
	ds_read_b128 v[6:9], v116 offset:27648
	ds_read_b128 v[44:47], v116 offset:27680
	ds_read_b64_tr_b16 v[96:97], v117 offset:20736
	ds_read_b64_tr_b16 v[98:99], v117 offset:21312
	ds_read_b64_tr_b16 v[218:219], v117 offset:23040
	ds_read_b64_tr_b16 v[220:221], v117 offset:23616
	ds_read_b128 v[222:225], v116 offset:27712
	ds_read_b64_tr_b16 v[226:227], v117 offset:25344
	ds_read_b64_tr_b16 v[228:229], v117 offset:25920
	ds_read_b128 v[230:233], v116 offset:27744
	s_waitcnt lgkmcnt(9)
	v_mfma_f32_32x32x16_bf16 v[2:17], v[2:5], v[6:9], 0
	v_readlane_b32 s4, v253, 55
	v_readlane_b32 s5, v253, 56
	s_waitcnt lgkmcnt(6)
	v_mfma_f32_32x32x16_bf16 v[2:17], v[96:99], v[44:47], v[2:17]
	s_waitcnt lgkmcnt(3)
	v_mfma_f32_32x32x16_bf16 v[2:17], v[218:221], v[222:225], v[2:17]
	s_waitcnt lgkmcnt(0)
	v_mfma_f32_32x32x16_bf16 v[2:17], v[226:229], v[230:233], v[2:17]
	s_nop 11
	v_cvt_pk_bf16_f32 v2, v2, v3
	v_cvt_pk_bf16_f32 v3, v4, v5
	v_cvt_pk_bf16_f32 v4, v6, v7
	v_cvt_pk_bf16_f32 v5, v8, v9
	ds_write2_b64 v141, v[2:3], v[4:5] offset0:128 offset1:130
	v_cvt_pk_bf16_f32 v2, v10, v11
	v_cvt_pk_bf16_f32 v3, v12, v13
	v_cvt_pk_bf16_f32 v4, v14, v15
	v_cvt_pk_bf16_f32 v5, v16, v17
	ds_write2_b64 v141, v[2:3], v[4:5] offset0:132 offset1:134
	s_waitcnt lgkmcnt(0)
	s_barrier
; DI int crow(int reg, int h) { return (reg & 3) + 8 * (reg >> 2) + 4 * h; }
; DI void dn_chain(const Params& p, int chain, char* lds) {
;     ...
;     for (int k = 1; k < 6; ++k) {
;       f32x16 M = mm64t<4>(R1, LS, R2, LS, wm, wn, r, h, lane);
;       st_transp(R4, LS, M, wm, wn, r, h);
;       __syncthreads();
;       f32x16 X = mm64t<4>(R2, LS, R4, LS, wm, wn, r, h, lane);
;       {
;         const int s = wn * 32 + r;
; #pragma unroll
;         for (int g = 0; g < 16; ++g) {
;           int c = wm * 32 + crow(g, h);
;           if ((c >> (k + 1)) == (s >> (k + 1)) && (c >> k) != (s >> k)) T[g] -= X[g];
;         }
;       }
;       __syncthreads();
;       st_transp(R2, LS, T, wm, wn, r, h);
;       __syncthreads();
;     }
	ds_read_b64_tr_b16 v[2:3], v117 offset:27648
	ds_read_b64_tr_b16 v[4:5], v117 offset:28224
	ds_read_b128 v[6:9], v112 offset:46080
	ds_read_b128 v[44:47], v112 offset:46112
	ds_read_b64_tr_b16 v[96:97], v117 offset:29952
	ds_read_b64_tr_b16 v[98:99], v117 offset:30528
	ds_read_b64_tr_b16 v[218:219], v117 offset:32256
	ds_read_b64_tr_b16 v[220:221], v117 offset:32832
	ds_read_b128 v[222:225], v112 offset:46144
	ds_read_b64_tr_b16 v[226:227], v117 offset:34560
	ds_read_b64_tr_b16 v[228:229], v117 offset:35136
	ds_read_b128 v[230:233], v112 offset:46176
	s_waitcnt lgkmcnt(9)
	v_mfma_f32_32x32x16_bf16 v[2:17], v[2:5], v[6:9], 0
	s_waitcnt lgkmcnt(6)
	v_mfma_f32_32x32x16_bf16 v[2:17], v[96:99], v[44:47], v[2:17]
	s_waitcnt lgkmcnt(3)
	v_mfma_f32_32x32x16_bf16 v[2:17], v[218:221], v[222:225], v[2:17]
	s_waitcnt lgkmcnt(0)
	s_barrier
	v_mfma_f32_32x32x16_bf16 v[2:17], v[226:229], v[230:233], v[2:17]
	s_nop 11
	v_sub_f32_e32 v2, v48, v2
	v_sub_f32_e32 v3, v49, v3
	v_cndmask_b32_e64 v48, v2, v48, s[16:17]
	v_sub_f32_e32 v2, v100, v4
	v_cndmask_b32_e64 v43, v3, v49, s[16:17]
	v_cndmask_b32_e64 v49, v2, v100, s[4:5]
	v_readlane_b32 s4, v253, 59
	v_sub_f32_e32 v2, v101, v5
	v_readlane_b32 s5, v253, 60
	s_nop 1
	v_cndmask_b32_e64 v100, v2, v101, s[4:5]
	v_readlane_b32 s4, v253, 63
	v_sub_f32_e32 v2, v102, v6
	v_readlane_b32 s5, v254, 0
	v_cvt_pk_bf16_f32 v3, v49, v100
	s_nop 0
	v_cndmask_b32_e64 v101, v2, v102, s[4:5]
	v_readlane_b32 s4, v254, 3
	v_sub_f32_e32 v2, v103, v7
	v_readlane_b32 s5, v254, 4
	s_nop 1
	v_cndmask_b32_e64 v102, v2, v103, s[4:5]
	v_readlane_b32 s4, v254, 7
	v_sub_f32_e32 v2, v142, v8
	v_readlane_b32 s5, v254, 8
	v_cvt_pk_bf16_f32 v4, v101, v102
	s_nop 0
	v_cndmask_b32_e64 v103, v2, v142, s[4:5]
	v_readlane_b32 s4, v254, 11
	v_sub_f32_e32 v2, v143, v9
	v_readlane_b32 s5, v254, 12
	s_nop 1
	v_cndmask_b32_e64 v142, v2, v143, s[4:5]
	v_readlane_b32 s4, v254, 15
	v_sub_f32_e32 v2, v144, v10
	v_readlane_b32 s5, v254, 16
	v_cvt_pk_bf16_f32 v5, v103, v142
	s_nop 0
	v_cndmask_b32_e64 v143, v2, v144, s[4:5]
	v_readlane_b32 s4, v254, 19
	v_sub_f32_e32 v2, v145, v11
	v_readlane_b32 s5, v254, 20
	s_nop 1
	v_cndmask_b32_e64 v144, v2, v145, s[4:5]
	v_readlane_b32 s4, v254, 23
	v_sub_f32_e32 v2, v146, v12
	v_readlane_b32 s5, v254, 24
	s_nop 1
	v_cndmask_b32_e64 v145, v2, v146, s[4:5]
	v_readlane_b32 s4, v254, 27
	v_sub_f32_e32 v2, v147, v13
	v_readlane_b32 s5, v254, 28
	s_nop 1
	v_cndmask_b32_e64 v146, v2, v147, s[4:5]
	v_readlane_b32 s4, v254, 31
	v_sub_f32_e32 v2, v148, v14
	v_readlane_b32 s5, v254, 32
	s_nop 1
	v_cndmask_b32_e64 v147, v2, v148, s[4:5]
	v_readlane_b32 s4, v254, 35
	v_sub_f32_e32 v2, v149, v15
	v_readlane_b32 s5, v254, 36
	s_nop 1
	v_cndmask_b32_e64 v148, v2, v149, s[4:5]
	v_readlane_b32 s4, v254, 39
	v_sub_f32_e32 v2, v150, v16
	v_readlane_b32 s5, v254, 40
	s_nop 1
	v_cndmask_b32_e64 v149, v2, v150, s[4:5]
	v_readlane_b32 s4, v254, 43
	v_sub_f32_e32 v2, v151, v17
	v_readlane_b32 s5, v254, 44
	s_nop 1
	v_cndmask_b32_e64 v150, v2, v151, s[4:5]
	v_cvt_pk_bf16_f32 v2, v48, v43
	ds_write2_b64 v42, v[2:3], v[4:5] offset0:128 offset1:130
	v_cvt_pk_bf16_f32 v2, v143, v144
	v_cvt_pk_bf16_f32 v3, v145, v146
	v_cvt_pk_bf16_f32 v4, v147, v148
	v_cvt_pk_bf16_f32 v5, v149, v150
	ds_write2_b64 v42, v[2:3], v[4:5] offset0:132 offset1:134
	s_waitcnt lgkmcnt(0)
	s_barrier
	ds_read_b64_tr_b16 v[2:3], v117 offset:18432
	ds_read_b64_tr_b16 v[4:5], v117 offset:19008
	ds_read_b128 v[6:9], v116 offset:27648
	ds_read_b128 v[44:47], v116 offset:27680
	ds_read_b64_tr_b16 v[96:97], v117 offset:20736
	ds_read_b64_tr_b16 v[98:99], v117 offset:21312
	ds_read_b64_tr_b16 v[218:219], v117 offset:23040
	ds_read_b64_tr_b16 v[220:221], v117 offset:23616
	ds_read_b128 v[222:225], v116 offset:27712
	ds_read_b64_tr_b16 v[226:227], v117 offset:25344
	ds_read_b64_tr_b16 v[228:229], v117 offset:25920
	ds_read_b128 v[230:233], v116 offset:27744
	s_waitcnt lgkmcnt(9)
	v_mfma_f32_32x32x16_bf16 v[2:17], v[2:5], v[6:9], 0
	v_readlane_b32 s4, v254, 45
	v_readlane_b32 s5, v254, 46
	s_waitcnt lgkmcnt(6)
	v_mfma_f32_32x32x16_bf16 v[2:17], v[96:99], v[44:47], v[2:17]
	s_waitcnt lgkmcnt(3)
	v_mfma_f32_32x32x16_bf16 v[2:17], v[218:221], v[222:225], v[2:17]
	s_waitcnt lgkmcnt(0)
	v_mfma_f32_32x32x16_bf16 v[2:17], v[226:229], v[230:233], v[2:17]
	s_nop 11
	v_cvt_pk_bf16_f32 v2, v2, v3
	v_cvt_pk_bf16_f32 v3, v4, v5
	v_cvt_pk_bf16_f32 v4, v6, v7
	v_cvt_pk_bf16_f32 v5, v8, v9
	ds_write2_b64 v141, v[2:3], v[4:5] offset0:128 offset1:130
	v_cvt_pk_bf16_f32 v2, v10, v11
	v_cvt_pk_bf16_f32 v3, v12, v13
	v_cvt_pk_bf16_f32 v4, v14, v15
	v_cvt_pk_bf16_f32 v5, v16, v17
	ds_write2_b64 v141, v[2:3], v[4:5] offset0:132 offset1:134
	s_waitcnt lgkmcnt(0)
	s_barrier
	ds_read_b64_tr_b16 v[2:3], v117 offset:27648
	ds_read_b64_tr_b16 v[4:5], v117 offset:28224
	ds_read_b128 v[6:9], v112 offset:46080
	ds_read_b128 v[44:47], v112 offset:46112
	ds_read_b64_tr_b16 v[96:97], v117 offset:29952
	ds_read_b64_tr_b16 v[98:99], v117 offset:30528
	ds_read_b64_tr_b16 v[218:219], v117 offset:32256
	ds_read_b64_tr_b16 v[220:221], v117 offset:32832
	ds_read_b128 v[222:225], v112 offset:46144
	ds_read_b64_tr_b16 v[226:227], v117 offset:34560
	ds_read_b64_tr_b16 v[228:229], v117 offset:35136
	ds_read_b128 v[230:233], v112 offset:46176
	s_waitcnt lgkmcnt(9)
	v_mfma_f32_32x32x16_bf16 v[2:17], v[2:5], v[6:9], 0
	s_waitcnt lgkmcnt(6)
	v_mfma_f32_32x32x16_bf16 v[2:17], v[96:99], v[44:47], v[2:17]
	s_waitcnt lgkmcnt(3)
	v_mfma_f32_32x32x16_bf16 v[2:17], v[218:221], v[222:225], v[2:17]
	s_waitcnt lgkmcnt(0)
	s_barrier
; DI int crow(int reg, int h) { return (reg & 3) + 8 * (reg >> 2) + 4 * h; }
; DI void dn_chain(const Params& p, int chain, char* lds) {
;     ...
;     for (int k = 1; k < 6; ++k) {
;       f32x16 M = mm64t<4>(R1, LS, R2, LS, wm, wn, r, h, lane);
;       st_transp(R4, LS, M, wm, wn, r, h);
;       __syncthreads();
;       f32x16 X = mm64t<4>(R2, LS, R4, LS, wm, wn, r, h, lane);
;       {
;         const int s = wn * 32 + r;
; #pragma unroll
;         for (int g = 0; g < 16; ++g) {
;           int c = wm * 32 + crow(g, h);
;           if ((c >> (k + 1)) == (s >> (k + 1)) && (c >> k) != (s >> k)) T[g] -= X[g];
;         }
;       }
;       __syncthreads();
;       st_transp(R2, LS, T, wm, wn, r, h);
;       __syncthreads();
;     }
	v_mfma_f32_32x32x16_bf16 v[2:17], v[226:229], v[230:233], v[2:17]
	s_nop 11
	v_sub_f32_e32 v2, v48, v2
	v_cndmask_b32_e64 v48, v2, v48, s[30:31]
	v_sub_f32_e32 v2, v101, v6
	v_cndmask_b32_e64 v101, v2, v101, s[4:5]
	v_readlane_b32 s4, v254, 47
	v_sub_f32_e32 v2, v102, v7
	v_readlane_b32 s5, v254, 48
	v_sub_f32_e32 v3, v43, v3
	v_sub_f32_e32 v4, v49, v4
	v_cndmask_b32_e64 v102, v2, v102, s[4:5]
	v_readlane_b32 s4, v254, 49
	v_sub_f32_e32 v2, v103, v8
	v_readlane_b32 s5, v254, 50
	v_sub_f32_e32 v5, v100, v5
	v_cndmask_b32_e64 v100, v5, v100, s[30:31]
	v_cndmask_b32_e64 v103, v2, v103, s[4:5]
	v_readlane_b32 s4, v254, 51
	v_sub_f32_e32 v2, v142, v9
	v_readlane_b32 s5, v254, 52
	v_cndmask_b32_e64 v49, v4, v49, s[30:31]
	v_cndmask_b32_e64 v43, v3, v43, s[30:31]
	v_cndmask_b32_e64 v142, v2, v142, s[4:5]
	v_readlane_b32 s4, v254, 53
	v_sub_f32_e32 v2, v143, v10
	v_readlane_b32 s5, v254, 54
	v_cvt_pk_bf16_f32 v3, v49, v100
	v_cvt_pk_bf16_f32 v4, v101, v102
	v_cndmask_b32_e64 v143, v2, v143, s[4:5]
	v_readlane_b32 s4, v254, 55
	v_sub_f32_e32 v2, v144, v11
	v_readlane_b32 s5, v254, 56
	v_cvt_pk_bf16_f32 v5, v103, v142
	s_nop 0
	v_cndmask_b32_e64 v144, v2, v144, s[4:5]
	v_readlane_b32 s4, v254, 57
	v_sub_f32_e32 v2, v145, v12
	v_readlane_b32 s5, v254, 58
	s_nop 1
	v_cndmask_b32_e64 v145, v2, v145, s[4:5]
	v_readlane_b32 s4, v254, 59
	v_sub_f32_e32 v2, v146, v13
	v_readlane_b32 s5, v254, 60
	s_nop 1
	v_cndmask_b32_e64 v146, v2, v146, s[4:5]
	v_readlane_b32 s4, v254, 61
	v_sub_f32_e32 v2, v147, v14
	v_readlane_b32 s5, v254, 62
	s_nop 1
	v_cndmask_b32_e64 v147, v2, v147, s[4:5]
	v_readlane_b32 s4, v254, 63
	v_sub_f32_e32 v2, v148, v15
	v_readlane_b32 s5, v255, 0
	s_nop 1
	v_cndmask_b32_e64 v148, v2, v148, s[4:5]
	v_readlane_b32 s4, v255, 1
	v_sub_f32_e32 v2, v149, v16
	v_readlane_b32 s5, v255, 2
	s_nop 1
	v_cndmask_b32_e64 v149, v2, v149, s[4:5]
	v_readlane_b32 s4, v255, 3
	v_sub_f32_e32 v2, v150, v17
	v_readlane_b32 s5, v255, 4
	s_nop 1
	v_cndmask_b32_e64 v150, v2, v150, s[4:5]
	v_cvt_pk_bf16_f32 v2, v48, v43
	ds_write2_b64 v42, v[2:3], v[4:5] offset0:128 offset1:130
	v_cvt_pk_bf16_f32 v2, v143, v144
	v_cvt_pk_bf16_f32 v3, v145, v146
	v_cvt_pk_bf16_f32 v4, v147, v148
	v_cvt_pk_bf16_f32 v5, v149, v150
	ds_write2_b64 v42, v[2:3], v[4:5] offset0:132 offset1:134
	s_waitcnt lgkmcnt(0)
	s_barrier
	ds_read_b64_tr_b16 v[2:3], v117 offset:18432
	ds_read_b64_tr_b16 v[4:5], v117 offset:19008
	ds_read_b128 v[6:9], v116 offset:27648
	ds_read_b128 v[44:47], v116 offset:27680
	ds_read_b64_tr_b16 v[96:97], v117 offset:20736
	ds_read_b64_tr_b16 v[98:99], v117 offset:21312
	ds_read_b64_tr_b16 v[218:219], v117 offset:23040
	ds_read_b64_tr_b16 v[220:221], v117 offset:23616
	ds_read_b128 v[222:225], v116 offset:27712
	ds_read_b64_tr_b16 v[226:227], v117 offset:25344
	ds_read_b64_tr_b16 v[228:229], v117 offset:25920
	ds_read_b128 v[230:233], v116 offset:27744
	s_waitcnt lgkmcnt(9)
	v_mfma_f32_32x32x16_bf16 v[2:17], v[2:5], v[6:9], 0
	v_readlane_b32 s4, v255, 5
	v_readlane_b32 s5, v255, 6
	s_waitcnt lgkmcnt(6)
	v_mfma_f32_32x32x16_bf16 v[2:17], v[96:99], v[44:47], v[2:17]
	s_waitcnt lgkmcnt(3)
	v_mfma_f32_32x32x16_bf16 v[2:17], v[218:221], v[222:225], v[2:17]
	s_waitcnt lgkmcnt(0)
	v_mfma_f32_32x32x16_bf16 v[2:17], v[226:229], v[230:233], v[2:17]
	s_nop 11
	v_cvt_pk_bf16_f32 v2, v2, v3
	v_cvt_pk_bf16_f32 v3, v4, v5
	v_cvt_pk_bf16_f32 v4, v6, v7
	v_cvt_pk_bf16_f32 v5, v8, v9
	ds_write2_b64 v141, v[2:3], v[4:5] offset0:128 offset1:130
	v_cvt_pk_bf16_f32 v2, v10, v11
	v_cvt_pk_bf16_f32 v3, v12, v13
	v_cvt_pk_bf16_f32 v4, v14, v15
	v_cvt_pk_bf16_f32 v5, v16, v17
	ds_write2_b64 v141, v[2:3], v[4:5] offset0:132 offset1:134
	s_waitcnt lgkmcnt(0)
	s_barrier
	ds_read_b64_tr_b16 v[2:3], v117 offset:27648
	ds_read_b64_tr_b16 v[4:5], v117 offset:28224
	ds_read_b128 v[6:9], v112 offset:46080
	ds_read_b128 v[44:47], v112 offset:46112
	ds_read_b64_tr_b16 v[96:97], v117 offset:29952
	ds_read_b64_tr_b16 v[98:99], v117 offset:30528
	ds_read_b64_tr_b16 v[218:219], v117 offset:32256
	ds_read_b64_tr_b16 v[220:221], v117 offset:32832
	ds_read_b128 v[222:225], v112 offset:46144
	ds_read_b64_tr_b16 v[226:227], v117 offset:34560
	ds_read_b64_tr_b16 v[228:229], v117 offset:35136
	ds_read_b128 v[230:233], v112 offset:46176
	s_waitcnt lgkmcnt(9)
	v_mfma_f32_32x32x16_bf16 v[2:17], v[2:5], v[6:9], 0
	s_waitcnt lgkmcnt(6)
	v_mfma_f32_32x32x16_bf16 v[2:17], v[96:99], v[44:47], v[2:17]
	s_waitcnt lgkmcnt(3)
	v_mfma_f32_32x32x16_bf16 v[2:17], v[218:221], v[222:225], v[2:17]
	s_waitcnt lgkmcnt(0)
	s_barrier
; DI int crow(int reg, int h) { return (reg & 3) + 8 * (reg >> 2) + 4 * h; }
; DI void dn_chain(const Params& p, int chain, char* lds) {
;     ...
;     for (int k = 1; k < 6; ++k) {
;       f32x16 M = mm64t<4>(R1, LS, R2, LS, wm, wn, r, h, lane);
;       st_transp(R4, LS, M, wm, wn, r, h);
;       __syncthreads();
;       f32x16 X = mm64t<4>(R2, LS, R4, LS, wm, wn, r, h, lane);
;       {
;         const int s = wn * 32 + r;
; #pragma unroll
;         for (int g = 0; g < 16; ++g) {
;           int c = wm * 32 + crow(g, h);
;           if ((c >> (k + 1)) == (s >> (k + 1)) && (c >> k) != (s >> k)) T[g] -= X[g];
;         }
;       }
;       __syncthreads();
;       st_transp(R2, LS, T, wm, wn, r, h);
;       __syncthreads();
;     }
	v_mfma_f32_32x32x16_bf16 v[2:17], v[226:229], v[230:233], v[2:17]
	s_nop 11
	v_sub_f32_e32 v2, v48, v2
	v_cndmask_b32_e64 v48, v2, v48, s[90:91]
	v_sub_f32_e32 v2, v101, v6
	v_cndmask_b32_e64 v101, v2, v101, s[4:5]
	v_readlane_b32 s4, v255, 7
	v_sub_f32_e32 v2, v102, v7
	v_readlane_b32 s5, v255, 8
	v_sub_f32_e32 v3, v43, v3
	v_sub_f32_e32 v4, v49, v4
	v_cndmask_b32_e64 v102, v2, v102, s[4:5]
	v_readlane_b32 s4, v255, 9
	v_sub_f32_e32 v2, v103, v8
	v_readlane_b32 s5, v255, 10
	v_sub_f32_e32 v5, v100, v5
	v_cndmask_b32_e64 v100, v5, v100, s[90:91]
	v_cndmask_b32_e64 v103, v2, v103, s[4:5]
	v_readlane_b32 s4, v255, 11
	v_sub_f32_e32 v2, v142, v9
	v_readlane_b32 s5, v255, 12
	v_cndmask_b32_e64 v49, v4, v49, s[90:91]
	v_cndmask_b32_e64 v43, v3, v43, s[90:91]
	v_cndmask_b32_e64 v142, v2, v142, s[4:5]
	v_readlane_b32 s4, v255, 13
	v_sub_f32_e32 v2, v143, v10
	v_readlane_b32 s5, v255, 14
	v_cvt_pk_bf16_f32 v3, v49, v100
	v_cvt_pk_bf16_f32 v4, v101, v102
	v_cndmask_b32_e64 v143, v2, v143, s[4:5]
	v_readlane_b32 s4, v255, 15
	v_sub_f32_e32 v2, v144, v11
	v_readlane_b32 s5, v255, 16
	v_cvt_pk_bf16_f32 v5, v103, v142
	s_nop 0
	v_cndmask_b32_e64 v144, v2, v144, s[4:5]
	v_readlane_b32 s4, v255, 17
	v_sub_f32_e32 v2, v145, v12
	v_readlane_b32 s5, v255, 18
	s_nop 1
	v_cndmask_b32_e64 v145, v2, v145, s[4:5]
	v_readlane_b32 s4, v255, 19
	v_sub_f32_e32 v2, v146, v13
	v_readlane_b32 s5, v255, 20
	s_nop 1
	v_cndmask_b32_e64 v146, v2, v146, s[4:5]
	v_readlane_b32 s4, v255, 21
	v_sub_f32_e32 v2, v147, v14
	v_readlane_b32 s5, v255, 22
	s_nop 1
	v_cndmask_b32_e64 v147, v2, v147, s[4:5]
	v_readlane_b32 s4, v255, 23
	v_sub_f32_e32 v2, v148, v15
	v_readlane_b32 s5, v255, 24
	s_nop 1
	v_cndmask_b32_e64 v148, v2, v148, s[4:5]
	v_readlane_b32 s4, v255, 25
	v_sub_f32_e32 v2, v149, v16
	v_readlane_b32 s5, v255, 26
	s_nop 1
	v_cndmask_b32_e64 v149, v2, v149, s[4:5]
	v_readlane_b32 s4, v255, 27
	v_sub_f32_e32 v2, v150, v17
	v_readlane_b32 s5, v255, 28
	s_nop 1
	v_cndmask_b32_e64 v150, v2, v150, s[4:5]
	v_cvt_pk_bf16_f32 v2, v48, v43
	ds_write2_b64 v42, v[2:3], v[4:5] offset0:128 offset1:130
	v_cvt_pk_bf16_f32 v2, v143, v144
	v_cvt_pk_bf16_f32 v3, v145, v146
	v_cvt_pk_bf16_f32 v4, v147, v148
	v_cvt_pk_bf16_f32 v5, v149, v150
	ds_write2_b64 v42, v[2:3], v[4:5] offset0:132 offset1:134
	s_waitcnt lgkmcnt(0)
	s_barrier
	ds_read_b64_tr_b16 v[2:3], v117 offset:18432
	ds_read_b64_tr_b16 v[4:5], v117 offset:19008
	ds_read_b128 v[6:9], v116 offset:27648
	ds_read_b128 v[44:47], v116 offset:27680
	ds_read_b64_tr_b16 v[96:97], v117 offset:20736
	ds_read_b64_tr_b16 v[98:99], v117 offset:21312
	ds_read_b64_tr_b16 v[218:219], v117 offset:23040
	ds_read_b64_tr_b16 v[220:221], v117 offset:23616
	ds_read_b128 v[222:225], v116 offset:27712
	ds_read_b64_tr_b16 v[226:227], v117 offset:25344
	ds_read_b64_tr_b16 v[228:229], v117 offset:25920
	ds_read_b128 v[230:233], v116 offset:27744
	s_waitcnt lgkmcnt(9)
	v_mfma_f32_32x32x16_bf16 v[2:17], v[2:5], v[6:9], 0
	v_readlane_b32 s4, v255, 29
	v_readlane_b32 s5, v255, 30
	s_waitcnt lgkmcnt(6)
	v_mfma_f32_32x32x16_bf16 v[2:17], v[96:99], v[44:47], v[2:17]
	s_waitcnt lgkmcnt(3)
	v_mfma_f32_32x32x16_bf16 v[2:17], v[218:221], v[222:225], v[2:17]
	s_waitcnt lgkmcnt(0)
	v_mfma_f32_32x32x16_bf16 v[2:17], v[226:229], v[230:233], v[2:17]
	s_nop 11
	v_cvt_pk_bf16_f32 v2, v2, v3
	v_cvt_pk_bf16_f32 v3, v4, v5
	v_cvt_pk_bf16_f32 v4, v6, v7
	v_cvt_pk_bf16_f32 v5, v8, v9
	ds_write2_b64 v141, v[2:3], v[4:5] offset0:128 offset1:130
	v_cvt_pk_bf16_f32 v2, v10, v11
	v_cvt_pk_bf16_f32 v3, v12, v13
	v_cvt_pk_bf16_f32 v4, v14, v15
	v_cvt_pk_bf16_f32 v5, v16, v17
	ds_write2_b64 v141, v[2:3], v[4:5] offset0:132 offset1:134
	s_waitcnt lgkmcnt(0)
	s_barrier
	ds_read_b64_tr_b16 v[2:3], v117 offset:27648
	ds_read_b64_tr_b16 v[4:5], v117 offset:28224
	ds_read_b128 v[6:9], v112 offset:46080
	ds_read_b128 v[44:47], v112 offset:46112
	ds_read_b64_tr_b16 v[96:97], v117 offset:29952
	ds_read_b64_tr_b16 v[98:99], v117 offset:30528
	ds_read_b64_tr_b16 v[218:219], v117 offset:32256
	ds_read_b64_tr_b16 v[220:221], v117 offset:32832
	ds_read_b128 v[222:225], v112 offset:46144
	ds_read_b64_tr_b16 v[226:227], v117 offset:34560
	ds_read_b64_tr_b16 v[228:229], v117 offset:35136
	ds_read_b128 v[230:233], v112 offset:46176
	s_waitcnt lgkmcnt(9)
	v_mfma_f32_32x32x16_bf16 v[2:17], v[2:5], v[6:9], 0
	s_waitcnt lgkmcnt(6)
	v_mfma_f32_32x32x16_bf16 v[2:17], v[96:99], v[44:47], v[2:17]
	s_waitcnt lgkmcnt(3)
	v_mfma_f32_32x32x16_bf16 v[2:17], v[218:221], v[222:225], v[2:17]
	s_waitcnt lgkmcnt(0)
	s_barrier
	v_mfma_f32_32x32x16_bf16 v[2:17], v[226:229], v[230:233], v[2:17]
	s_nop 11
	v_sub_f32_e32 v2, v48, v2
	v_cndmask_b32_e64 v48, v2, v48, s[80:81]
	v_sub_f32_e32 v2, v143, v10
	v_cndmask_b32_e64 v143, v2, v143, s[4:5]
	v_readlane_b32 s4, v255, 31
	v_sub_f32_e32 v2, v144, v11
	v_readlane_b32 s5, v255, 32
	v_sub_f32_e32 v3, v43, v3
	v_sub_f32_e32 v4, v49, v4
	v_cndmask_b32_e64 v144, v2, v144, s[4:5]
	v_sub_f32_e32 v2, v145, v12
	v_cndmask_b32_e64 v145, v2, v145, s[10:11]
	v_sub_f32_e32 v2, v146, v13
	v_cndmask_b32_e64 v146, v2, v146, s[34:35]
	v_sub_f32_e32 v2, v147, v14
	v_cndmask_b32_e64 v147, v2, v147, s[36:37]
	v_sub_f32_e32 v2, v148, v15
	v_sub_f32_e32 v5, v100, v5
	v_sub_f32_e32 v6, v101, v6
	v_sub_f32_e32 v7, v102, v7
	v_sub_f32_e32 v8, v103, v8
	v_sub_f32_e32 v9, v142, v9
	v_cndmask_b32_e64 v148, v2, v148, s[12:13]
	v_sub_f32_e32 v2, v149, v16
	v_cndmask_b32_e64 v142, v9, v142, s[80:81]
	v_cndmask_b32_e64 v103, v8, v103, s[80:81]
	v_cndmask_b32_e64 v102, v7, v102, s[80:81]
	v_cndmask_b32_e64 v101, v6, v101, s[80:81]
	v_cndmask_b32_e64 v100, v5, v100, s[80:81]
	v_cndmask_b32_e64 v49, v4, v49, s[80:81]
	v_cndmask_b32_e64 v43, v3, v43, s[80:81]
	v_cndmask_b32_e64 v149, v2, v149, s[28:29]
	v_sub_f32_e32 v2, v150, v17
	v_cndmask_b32_e64 v150, v2, v150, s[0:1]
	v_cvt_pk_bf16_f32 v2, v48, v43
	v_cvt_pk_bf16_f32 v3, v49, v100
	v_cvt_pk_bf16_f32 v4, v101, v102
	v_cvt_pk_bf16_f32 v5, v103, v142
	ds_write2_b64 v42, v[2:3], v[4:5] offset0:128 offset1:130
	v_cvt_pk_bf16_f32 v2, v143, v144
	v_cvt_pk_bf16_f32 v3, v145, v146
	v_cvt_pk_bf16_f32 v4, v147, v148
	v_cvt_pk_bf16_f32 v5, v149, v150
	ds_write2_b64 v42, v[2:3], v[4:5] offset0:132 offset1:134
	s_waitcnt lgkmcnt(0)
	s_barrier
; DI int crow(int reg, int h) { return (reg & 3) + 8 * (reg >> 2) + 4 * h; }
; DI void dn_chain(const Params& p, int chain, char* lds) {
;     ...
;     for (int k = 1; k < 6; ++k) {
;       f32x16 M = mm64t<4>(R1, LS, R2, LS, wm, wn, r, h, lane);
;       st_transp(R4, LS, M, wm, wn, r, h);
;       __syncthreads();
;       f32x16 X = mm64t<4>(R2, LS, R4, LS, wm, wn, r, h, lane);
;       {
;         const int s = wn * 32 + r;
; #pragma unroll
;         for (int g = 0; g < 16; ++g) {
;           int c = wm * 32 + crow(g, h);
;           if ((c >> (k + 1)) == (s >> (k + 1)) && (c >> k) != (s >> k)) T[g] -= X[g];
;         }
;       }
;       __syncthreads();
;       st_transp(R2, LS, T, wm, wn, r, h);
;       __syncthreads();
;     }
;     {
;       const float fb0 = bt[lc], fk0 = fb0 * __expf(gc[lc]);
;       const float fb1 = bt[lc + 32], fk1 = fb1 * __expf(gc[lc + 32]);
;       st8s(R1 + lc * LS + lp, ck0, fk0);
;       st8s(R1 + (lc + 32) * LS + lp, ck1, fk1);
;       st8s(R3 + lc * LS + lp, cv0, fb0);
;       st8s(R3 + (lc + 32) * LS + lp, cv1, fb1);
;     }
	ds_read_b64_tr_b16 v[2:3], v117 offset:18432
	ds_read_b64_tr_b16 v[4:5], v117 offset:19008
	ds_read_b128 v[6:9], v116 offset:27648
	ds_read_b128 v[44:47], v116 offset:27680
	ds_read_b64_tr_b16 v[96:97], v117 offset:20736
	ds_read_b64_tr_b16 v[98:99], v117 offset:21312
	ds_read_b64_tr_b16 v[218:219], v117 offset:23040
	ds_read_b64_tr_b16 v[220:221], v117 offset:23616
	ds_read_b128 v[222:225], v116 offset:27712
	ds_read_b64_tr_b16 v[226:227], v117 offset:25344
	ds_read_b64_tr_b16 v[228:229], v117 offset:25920
	ds_read_b128 v[230:233], v116 offset:27744
	s_waitcnt lgkmcnt(9)
	v_mfma_f32_32x32x16_bf16 v[2:17], v[2:5], v[6:9], 0
	s_waitcnt lgkmcnt(6)
	v_mfma_f32_32x32x16_bf16 v[2:17], v[96:99], v[44:47], v[2:17]
	s_waitcnt lgkmcnt(3)
	v_mfma_f32_32x32x16_bf16 v[2:17], v[218:221], v[222:225], v[2:17]
	s_waitcnt lgkmcnt(0)
	v_mfma_f32_32x32x16_bf16 v[2:17], v[226:229], v[230:233], v[2:17]
	s_nop 11
	v_cvt_pk_bf16_f32 v2, v2, v3
	v_cvt_pk_bf16_f32 v3, v4, v5
	v_cvt_pk_bf16_f32 v4, v6, v7
	v_cvt_pk_bf16_f32 v5, v8, v9
	ds_write2_b64 v141, v[2:3], v[4:5] offset0:128 offset1:130
	v_cvt_pk_bf16_f32 v2, v10, v11
	v_cvt_pk_bf16_f32 v3, v12, v13
	v_cvt_pk_bf16_f32 v4, v14, v15
	v_cvt_pk_bf16_f32 v5, v16, v17
	ds_write2_b64 v141, v[2:3], v[4:5] offset0:132 offset1:134
	s_waitcnt lgkmcnt(0)
	s_barrier
	ds_read_b64_tr_b16 v[2:3], v117 offset:27648
	ds_read_b64_tr_b16 v[4:5], v117 offset:28224
	ds_read_b128 v[6:9], v112 offset:46080
	ds_read_b128 v[44:47], v112 offset:46112
	ds_read_b64_tr_b16 v[96:97], v117 offset:29952
	ds_read_b64_tr_b16 v[98:99], v117 offset:30528
	ds_read_b64_tr_b16 v[218:219], v117 offset:32256
	ds_read_b64_tr_b16 v[220:221], v117 offset:32832
	ds_read_b128 v[222:225], v112 offset:46144
	ds_read_b64_tr_b16 v[226:227], v117 offset:34560
	ds_read_b64_tr_b16 v[228:229], v117 offset:35136
	ds_read_b128 v[230:233], v112 offset:46176
	s_waitcnt lgkmcnt(9)
	v_mfma_f32_32x32x16_bf16 v[2:17], v[2:5], v[6:9], 0
	s_waitcnt lgkmcnt(6)
	v_mfma_f32_32x32x16_bf16 v[2:17], v[96:99], v[44:47], v[2:17]
	s_waitcnt lgkmcnt(3)
	v_mfma_f32_32x32x16_bf16 v[2:17], v[218:221], v[222:225], v[2:17]
	s_waitcnt lgkmcnt(0)
	s_barrier
	v_mfma_f32_32x32x16_bf16 v[2:17], v[226:229], v[230:233], v[2:17]
	v_lshlrev_b32_e32 v44, 16, v31
	v_and_b32_e32 v45, 0xffff0000, v31
	v_lshlrev_b32_e32 v46, 16, v32
	v_and_b32_e32 v47, 0xffff0000, v32
	v_lshlrev_b32_e32 v96, 16, v33
	v_and_b32_e32 v97, 0xffff0000, v33
	v_lshlrev_b32_e32 v98, 16, v27
	s_nop 4
	v_sub_f32_e32 v2, v48, v2
	v_sub_f32_e32 v3, v43, v3
	v_sub_f32_e32 v4, v49, v4
	v_sub_f32_e32 v5, v100, v5
	v_sub_f32_e32 v6, v101, v6
	v_sub_f32_e32 v7, v102, v7
	v_sub_f32_e32 v8, v103, v8
	v_sub_f32_e32 v9, v142, v9
	v_sub_f32_e32 v10, v143, v10
	v_sub_f32_e32 v11, v144, v11
	v_sub_f32_e32 v12, v145, v12
	v_sub_f32_e32 v13, v146, v13
	v_sub_f32_e32 v14, v147, v14
	v_sub_f32_e32 v15, v148, v15
	v_sub_f32_e32 v16, v149, v16
	v_sub_f32_e32 v17, v150, v17
	v_cndmask_b32_e64 v9, v9, v142, s[44:45]
	v_cndmask_b32_e64 v8, v8, v103, s[44:45]
	v_cndmask_b32_e64 v7, v7, v102, s[44:45]
	v_cndmask_b32_e64 v6, v6, v101, s[44:45]
	v_cndmask_b32_e64 v5, v5, v100, s[44:45]
	v_cndmask_b32_e64 v4, v4, v49, s[44:45]
	v_cndmask_b32_e64 v3, v3, v43, s[44:45]
	v_cndmask_b32_e64 v2, v2, v48, s[44:45]
	v_cndmask_b32_e64 v17, v17, v150, s[44:45]
	v_cndmask_b32_e64 v16, v16, v149, s[44:45]
	v_cndmask_b32_e64 v15, v15, v148, s[44:45]
	v_cndmask_b32_e64 v14, v14, v147, s[44:45]
	v_cndmask_b32_e64 v13, v13, v146, s[44:45]
	v_cndmask_b32_e64 v12, v12, v145, s[44:45]
	v_cndmask_b32_e64 v11, v11, v144, s[44:45]
	v_cndmask_b32_e64 v10, v10, v143, s[44:45]
	v_cvt_pk_bf16_f32 v2, v2, v3
	v_cvt_pk_bf16_f32 v3, v4, v5
	v_cvt_pk_bf16_f32 v4, v6, v7
	v_cvt_pk_bf16_f32 v5, v8, v9
	ds_write2_b64 v42, v[2:3], v[4:5] offset0:128 offset1:130
	v_cvt_pk_bf16_f32 v2, v10, v11
	v_cvt_pk_bf16_f32 v3, v12, v13
	v_cvt_pk_bf16_f32 v4, v14, v15
	v_cvt_pk_bf16_f32 v5, v16, v17
	ds_write2_b64 v42, v[2:3], v[4:5] offset0:132 offset1:134
	v_add_u32_e32 v2, 0xfc00, v119
	s_waitcnt lgkmcnt(0)
	s_barrier
	ds_read2_b32 v[6:7], v2 offset0:64 offset1:96
	ds_read2_b32 v[2:3], v2 offset1:32
	v_lshlrev_b32_e32 v42, 16, v30
	v_and_b32_e32 v43, 0xffff0000, v30
	v_lshlrev_b32_e32 v48, 16, v26
	v_and_b32_e32 v49, 0xffff0000, v26
	s_waitcnt lgkmcnt(0)
	v_mul_f32_e32 v2, 0x3fb8aa3b, v2
	v_exp_f32_e32 v2, v2
	v_and_b32_e32 v99, 0xffff0000, v27
	v_lshlrev_b32_e32 v100, 16, v28
	v_and_b32_e32 v101, 0xffff0000, v28
	v_mul_f32_e32 v8, v6, v2
	v_mul_f32_e32 v2, 0x3fb8aa3b, v3
	v_exp_f32_e32 v2, v2
	v_pk_mul_f32 v[4:5], v[8:9], v[44:45] op_sel_hi:[0,1]
	v_lshlrev_b32_e32 v102, 16, v29
	v_and_b32_e32 v103, 0xffff0000, v29
	v_mul_f32_e32 v10, v7, v2
	v_pk_mul_f32 v[2:3], v[8:9], v[42:43] op_sel_hi:[0,1]
	v_cvt_pk_bf16_f32 v2, v2, v3
	v_cvt_pk_bf16_f32 v3, v4, v5
	v_pk_mul_f32 v[4:5], v[8:9], v[46:47] op_sel_hi:[0,1]
	v_pk_mul_f32 v[8:9], v[8:9], v[96:97] op_sel_hi:[0,1]
	v_cvt_pk_bf16_f32 v4, v4, v5
	v_cvt_pk_bf16_f32 v5, v8, v9
	ds_write_b128 v120, v[2:5] offset:18432
	v_pk_mul_f32 v[2:3], v[10:11], v[48:49] op_sel_hi:[0,1]
	v_pk_mul_f32 v[4:5], v[10:11], v[98:99] op_sel_hi:[0,1]
	v_cvt_pk_bf16_f32 v2, v2, v3
	v_cvt_pk_bf16_f32 v3, v4, v5
	v_pk_mul_f32 v[4:5], v[10:11], v[100:101] op_sel_hi:[0,1]
	v_pk_mul_f32 v[8:9], v[10:11], v[102:103] op_sel_hi:[0,1]
	v_cvt_pk_bf16_f32 v4, v4, v5
	v_cvt_pk_bf16_f32 v5, v8, v9
	ds_write_b128 v110, v[2:5] offset:18432
	v_lshlrev_b32_e32 v2, 16, v22
	v_and_b32_e32 v3, 0xffff0000, v22
	v_lshlrev_b32_e32 v4, 16, v23
	v_and_b32_e32 v5, 0xffff0000, v23
	v_pk_mul_f32 v[2:3], v[6:7], v[2:3] op_sel_hi:[0,1]
	v_pk_mul_f32 v[4:5], v[6:7], v[4:5] op_sel_hi:[0,1]
	v_cvt_pk_bf16_f32 v2, v2, v3
	v_cvt_pk_bf16_f32 v3, v4, v5
	v_lshlrev_b32_e32 v4, 16, v24
	v_and_b32_e32 v5, 0xffff0000, v24
	v_lshlrev_b32_e32 v8, 16, v25
	v_and_b32_e32 v9, 0xffff0000, v25
	v_pk_mul_f32 v[4:5], v[6:7], v[4:5] op_sel_hi:[0,1]
	v_pk_mul_f32 v[8:9], v[6:7], v[8:9] op_sel_hi:[0,1]
	v_cvt_pk_bf16_f32 v4, v4, v5
	v_cvt_pk_bf16_f32 v5, v8, v9
	ds_write_b128 v120, v[2:5] offset:36864
	s_waitcnt vmcnt(6)
	v_lshlrev_b32_e32 v2, 16, v18
	v_and_b32_e32 v3, 0xffff0000, v18
	v_mov_b32_e32 v6, v7
	v_lshlrev_b32_e32 v4, 16, v19
	v_and_b32_e32 v5, 0xffff0000, v19
	v_pk_mul_f32 v[2:3], v[6:7], v[2:3] op_sel_hi:[0,1]
	v_pk_mul_f32 v[4:5], v[6:7], v[4:5] op_sel_hi:[0,1]
	v_cvt_pk_bf16_f32 v2, v2, v3
	v_cvt_pk_bf16_f32 v3, v4, v5
	v_lshlrev_b32_e32 v4, 16, v20
	v_and_b32_e32 v5, 0xffff0000, v20
	v_lshlrev_b32_e32 v8, 16, v21
	v_and_b32_e32 v9, 0xffff0000, v21
	v_pk_mul_f32 v[4:5], v[6:7], v[4:5] op_sel_hi:[0,1]
	v_pk_mul_f32 v[6:7], v[6:7], v[8:9] op_sel_hi:[0,1]
	v_cvt_pk_bf16_f32 v4, v4, v5
	v_cvt_pk_bf16_f32 v5, v6, v7
	ds_write_b128 v110, v[2:5] offset:36864
	s_waitcnt lgkmcnt(0)
	s_barrier
; DI int crow(int reg, int h) { return (reg & 3) + 8 * (reg >> 2) + 4 * h; }
; DI void dn_chain(const Params& p, int chain, char* lds) {
;     ...
;     f32x16 W = mm64x<4, true, true>(R2, LS, R1, LS, wm, wn, r, h, lane);
;     f32x16 U = mm64x<4, true, true>(R2, LS, R3, LS, wm, wn, r, h, lane);
;     st_transp(R4, LS, W, wm, wn, r, h);
;     __syncthreads();
;     {
;       f32x16 ws = mm64t<4>(R4, LS, St, LS, wm, wn, r, h, lane);
; #pragma unroll
;       for (int g = 0; g < 16; ++g) U[g] -= ws[g];
;       st_transp(R1, LS, U, wm, wn, r, h);
;     }
;     *(uint4*)(R2 + lc * LS + lp) = cq0;
;     *(uint4*)(R2 + (lc + 32) * LS + lp) = cq1;
;     st8s(R5 + lc * LS + lp, ck0, __expf(gl - gc[lc]));
;     st8s(R5 + (lc + 32) * LS + lp, ck1, __expf(gl - gc[lc + 32]));
;     __syncthreads();
;     {
;       f32x16 qk = mm64<4>(R2, LS, kA, LS, wm, wn, r, h);
;       const int s = wn * 32 + r;
;       const float gs = gc[s];
; #pragma unroll
;       for (int g = 0; g < 16; ++g) {
;         int c = wm * 32 + crow(g, h);
;         qk[g] = (s <= c) ? qk[g] * __expf(gc[c] - gs) : 0.f;
	ds_read_b64_tr_b16 v[18:19], v117 offset:27648
	ds_read_b64_tr_b16 v[20:21], v117 offset:28224
	ds_read_b64_tr_b16 v[2:3], v138 offset:18432
	ds_read_b64_tr_b16 v[4:5], v138 offset:19008
	s_waitcnt lgkmcnt(0)
	v_mfma_f32_32x32x16_bf16 v[2:17], v[18:21], v[2:5], 0
	ds_read_b64_tr_b16 v[142:143], v117 offset:29952
	ds_read_b64_tr_b16 v[144:145], v117 offset:30528
	ds_read_b64_tr_b16 v[22:23], v138 offset:20736
	ds_read_b64_tr_b16 v[24:25], v138 offset:21312
	s_waitcnt lgkmcnt(0)
	v_mfma_f32_32x32x16_bf16 v[2:17], v[142:145], v[22:25], v[2:17]
	ds_read_b64_tr_b16 v[146:147], v117 offset:32256
	ds_read_b64_tr_b16 v[148:149], v117 offset:32832
	ds_read_b64_tr_b16 v[22:23], v138 offset:23040
	ds_read_b64_tr_b16 v[24:25], v138 offset:23616
	s_waitcnt lgkmcnt(0)
	v_mfma_f32_32x32x16_bf16 v[2:17], v[146:149], v[22:25], v[2:17]
	ds_read_b64_tr_b16 v[150:151], v117 offset:34560
	ds_read_b64_tr_b16 v[152:153], v117 offset:35136
	ds_read_b64_tr_b16 v[22:23], v138 offset:25344
	ds_read_b64_tr_b16 v[24:25], v138 offset:25920
	s_waitcnt lgkmcnt(0)
	v_mfma_f32_32x32x16_bf16 v[2:17], v[150:153], v[22:25], v[2:17]
	ds_read_b64_tr_b16 v[22:23], v138 offset:36864
	ds_read_b64_tr_b16 v[24:25], v138 offset:37440
	ds_read_b64_tr_b16 v[154:155], v138 offset:39168
	ds_read_b64_tr_b16 v[156:157], v138 offset:39744
	s_waitcnt lgkmcnt(2)
	v_mfma_f32_32x32x16_bf16 v[18:33], v[18:21], v[22:25], 0
	s_nop 5
	v_cvt_pk_bf16_f32 v2, v2, v3
	v_cvt_pk_bf16_f32 v3, v4, v5
	v_cvt_pk_bf16_f32 v4, v6, v7
	v_cvt_pk_bf16_f32 v5, v8, v9
	s_waitcnt lgkmcnt(0)
	v_mfma_f32_32x32x16_bf16 v[18:33], v[142:145], v[154:157], v[18:33]
	ds_read_b64_tr_b16 v[142:143], v138 offset:41472
	ds_read_b64_tr_b16 v[144:145], v138 offset:42048
	s_waitcnt lgkmcnt(0)
	v_mfma_f32_32x32x16_bf16 v[18:33], v[146:149], v[142:145], v[18:33]
	ds_read_b64_tr_b16 v[142:143], v138 offset:43776
	ds_read_b64_tr_b16 v[144:145], v138 offset:44352
	ds_write2_b64 v141, v[2:3], v[4:5] offset0:128 offset1:130
	v_cvt_pk_bf16_f32 v2, v10, v11
	v_cvt_pk_bf16_f32 v3, v12, v13
	v_cvt_pk_bf16_f32 v4, v14, v15
	v_cvt_pk_bf16_f32 v5, v16, v17
	ds_write2_b64 v141, v[2:3], v[4:5] offset0:132 offset1:134
	s_waitcnt lgkmcnt(2)
	v_mfma_f32_32x32x16_bf16 v[18:33], v[150:153], v[142:145], v[18:33]
	s_waitcnt lgkmcnt(0)
	s_barrier
	ds_read_b64_tr_b16 v[2:3], v117 offset:46080
	ds_read_b64_tr_b16 v[4:5], v117 offset:46656
	ds_read_b128 v[6:9], v112 offset:9216
	ds_read_b128 v[142:145], v112 offset:9248
	ds_read_b64_tr_b16 v[146:147], v117 offset:48384
	ds_read_b64_tr_b16 v[148:149], v117 offset:48960
	s_waitcnt lgkmcnt(3)
	v_mfma_f32_32x32x16_bf16 v[2:17], v[2:5], v[6:9], 0
	s_waitcnt lgkmcnt(0)
	v_mfma_f32_32x32x16_bf16 v[2:17], v[146:149], v[142:145], v[2:17]
	ds_read_b64_tr_b16 v[142:143], v117 offset:50688
	ds_read_b64_tr_b16 v[144:145], v117 offset:51264
	ds_read_b128 v[146:149], v112 offset:9280
	s_waitcnt lgkmcnt(0)
	v_mfma_f32_32x32x16_bf16 v[2:17], v[142:145], v[146:149], v[2:17]
	ds_read_b64_tr_b16 v[142:143], v117 offset:52992
	ds_read_b64_tr_b16 v[144:145], v117 offset:53568
	ds_read_b128 v[146:149], v112 offset:9312
	s_waitcnt lgkmcnt(0)
	v_mfma_f32_32x32x16_bf16 v[2:17], v[142:145], v[146:149], v[2:17]
	s_nop 11
	v_sub_f32_e32 v9, v25, v9
	v_sub_f32_e32 v8, v24, v8
	v_sub_f32_e32 v7, v23, v7
	v_sub_f32_e32 v6, v22, v6
	v_sub_f32_e32 v5, v21, v5
	v_sub_f32_e32 v4, v20, v4
	v_sub_f32_e32 v3, v19, v3
	v_sub_f32_e32 v2, v18, v2
	v_sub_f32_e32 v17, v33, v17
	v_sub_f32_e32 v16, v32, v16
	v_sub_f32_e32 v15, v31, v15
	v_sub_f32_e32 v14, v30, v14
	v_sub_f32_e32 v13, v29, v13
	v_sub_f32_e32 v12, v28, v12
	v_sub_f32_e32 v11, v27, v11
	v_sub_f32_e32 v10, v26, v10
	v_cvt_pk_bf16_f32 v2, v2, v3
	v_cvt_pk_bf16_f32 v3, v4, v5
	v_cvt_pk_bf16_f32 v4, v6, v7
	v_cvt_pk_bf16_f32 v5, v8, v9
	ds_write2_b64 v140, v[2:3], v[4:5] offset1:2
	v_cvt_pk_bf16_f32 v2, v10, v11
	v_cvt_pk_bf16_f32 v3, v12, v13
	v_cvt_pk_bf16_f32 v4, v14, v15
	v_cvt_pk_bf16_f32 v5, v16, v17
	ds_write2_b64 v140, v[2:3], v[4:5] offset0:4 offset1:6
	ds_write_b128 v109, v[34:37] offset:27648
	ds_write_b128 v110, v[38:41] offset:27648
	ds_read_b32 v2, v119 offset:64512
	s_waitcnt lgkmcnt(0)
	v_sub_f32_e32 v2, v0, v2
	v_mul_f32_e32 v2, 0x3fb8aa3b, v2
	v_exp_f32_e32 v6, v2
	s_nop 0
	v_pk_mul_f32 v[2:3], v[6:7], v[42:43] op_sel_hi:[0,1]
	v_pk_mul_f32 v[4:5], v[6:7], v[44:45] op_sel_hi:[0,1]
	v_cvt_pk_bf16_f32 v2, v2, v3
	v_cvt_pk_bf16_f32 v3, v4, v5
	v_pk_mul_f32 v[4:5], v[6:7], v[46:47] op_sel_hi:[0,1]
	v_pk_mul_f32 v[6:7], v[6:7], v[96:97] op_sel_hi:[0,1]
	v_cvt_pk_bf16_f32 v4, v4, v5
	v_cvt_pk_bf16_f32 v5, v6, v7
	ds_write_b128 v109, v[2:5] offset:55296
	ds_read_b32 v2, v119 offset:64640
	s_waitcnt lgkmcnt(0)
	v_sub_f32_e32 v2, v0, v2
	v_mul_f32_e32 v2, 0x3fb8aa3b, v2
	v_exp_f32_e32 v6, v2
	s_nop 0
	v_pk_mul_f32 v[2:3], v[6:7], v[48:49] op_sel_hi:[0,1]
	v_pk_mul_f32 v[4:5], v[6:7], v[98:99] op_sel_hi:[0,1]
	v_cvt_pk_bf16_f32 v2, v2, v3
	v_cvt_pk_bf16_f32 v3, v4, v5
	v_pk_mul_f32 v[4:5], v[6:7], v[100:101] op_sel_hi:[0,1]
	v_pk_mul_f32 v[6:7], v[6:7], v[102:103] op_sel_hi:[0,1]
	v_cvt_pk_bf16_f32 v4, v4, v5
	v_cvt_pk_bf16_f32 v5, v6, v7
	ds_write_b128 v110, v[2:5] offset:55296
	s_waitcnt lgkmcnt(0)
	s_barrier
	ds_read_b128 v[2:5], v111 offset:27648
	ds_read_b128 v[18:21], v111 offset:27680
	ds_read_b128 v[6:9], v112
	ds_read_b128 v[22:25], v112 offset:32
	s_waitcnt lgkmcnt(1)
	v_mfma_f32_32x32x16_bf16 v[2:17], v[2:5], v[6:9], 0
	s_waitcnt lgkmcnt(0)
	v_mfma_f32_32x32x16_bf16 v[2:17], v[18:21], v[22:25], v[2:17]
	ds_read_b128 v[18:21], v111 offset:27712
	ds_read_b128 v[22:25], v112 offset:64
	s_waitcnt lgkmcnt(0)
	v_mfma_f32_32x32x16_bf16 v[2:17], v[18:21], v[22:25], v[2:17]
	ds_read_b128 v[18:21], v111 offset:27744
	ds_read_b128 v[22:25], v112 offset:96
	s_waitcnt lgkmcnt(0)
	v_mfma_f32_32x32x16_bf16 v[2:17], v[18:21], v[22:25], v[2:17]
	ds_read_b32 v18, v113 offset:64512
	ds_read_b128 v[218:221], v122 offset:64512
	ds_read_b128 v[222:225], v122 offset:64544
	ds_read_b128 v[226:229], v122 offset:64576
	ds_read_b128 v[230:233], v122 offset:64608
	s_waitcnt lgkmcnt(0)
	s_and_saveexec_b64 s[4:5], s[22:23]
	s_cbranch_execz .LBB0_695
	v_sub_f32_e32 v19, v218, v18
	v_mul_f32_e32 v19, 0x3fb8aa3b, v19
	v_exp_f32_e32 v19, v19
	s_nop 3
	v_mul_f32_e32 v139, v2, v19

; DI void gemm_phase(const Params& p, int layer, int mode, int nrows, char* lds_all) {
;     ...
;       for (int idx = tid; idx < 128 * 64; idx += 512) {
;         const int rr = idx >> 6, c4 = (idx & 63) * 4;
;         const int row = m0 + half * 128 + rr, col = n0 + c4;
;         float4 v = *(const float4*)(Cs + rr * CSW + c4);
;         {
;           const float* gate = mod + rowb(row) * 6144 + (mode == 1 ? 2 : 5) * 1024 + col;
;           float4 gt = *(const float4*)gate;
;           const float* res = (mode == 1 && layer == 0) ? xrow0(p, row) : xrow(p, row);
;           float4 xr = *(const float4*)(res + col);
;           if (!(mode == 1 && layer == 0)) {
;             const float2 st = ((const float2*)(p.ws + O_ST))[row];
;             const float* lg_ = (mode == 3) ? p.ln1_g + layer * DM : p.ln2_g + (layer - 1) * DM;
;             const float* lb_ = (mode == 3) ? p.ln1_b + layer * DM : p.ln2_b + (layer - 1) * DM;
;             const float4 lg4 = *(const float4*)(lg_ + col), lb4 = *(const float4*)(lb_ + col);
;             xr.x = (xr.x - st.x) * st.y * lg4.x + lb4.x; xr.y = (xr.y - st.x) * st.y * lg4.y + lb4.y;
;             xr.z = (xr.z - st.x) * st.y * lg4.z + lb4.z; xr.w = (xr.w - st.x) * st.y * lg4.w + lb4.w;
;           }
;           float4 o;
;           o.x = DN_ALPHA * xr.x + gt.x * v.x; o.y = DN_ALPHA * xr.y + gt.y * v.y;
;           o.z = DN_ALPHA * xr.z + gt.z * v.z; o.w = DN_ALPHA * xr.w + gt.w * v.w;
;           *(float4*)(xrow(p, row) + col) = o;
;         }
.LBB0_798:
	v_ashrrev_i32_e32 v136, 6, v236
	v_add_u32_e32 v146, s29, v136
	v_cmp_gt_i32_e32 vcc, s55, v146
	v_mov_b32_e32 v134, s33
	v_mov_b32_e32 v135, s95
	v_min_i32_e32 v130, 0x10000, v146
	v_cndmask_b32_e32 v145, v134, v135, vcc
	v_mov_b32_e32 v134, s57
	v_mov_b32_e32 v135, s94
	v_and_b32_e32 v137, 0xfc, v235
	v_ashrrev_i32_e32 v130, 12, v130
	v_cndmask_b32_e32 v144, v134, v135, vcc
	v_mov_b32_e32 v134, s52
	v_mov_b32_e32 v135, s48
	v_or_b32_e32 v142, s28, v137
	v_mul_i32_i24_e32 v130, 0x1800, v130
	v_add_u32_e32 v132, 0xffff0000, v146
	v_ashrrev_i32_e32 v147, 31, v146
	v_cndmask_b32_e32 v134, v134, v135, vcc
	v_mov_b32_e32 v135, s53
	v_mov_b32_e32 v138, s49
	v_ashrrev_i32_e32 v131, 31, v130
	v_ashrrev_i32_e32 v143, 31, v142
	v_cndmask_b32_e32 v133, 0, v147, vcc
	v_cndmask_b32_e32 v132, v132, v146, vcc
	v_cndmask_b32_e32 v135, v135, v138, vcc
	v_lshl_add_u64 v[130:131], v[130:131], 2, s[2:3]
	v_lshlrev_b64 v[150:151], 2, v[142:143]
	v_cndmask_b32_e64 v135, v145, v135, s[68:69]
	v_cndmask_b32_e64 v134, v144, v134, s[68:69]
	v_lshlrev_b64 v[148:149], 12, v[132:133]
	v_lshl_add_u64 v[130:131], v[130:131], 0, v[150:151]
	v_lshl_add_u64 v[132:133], v[134:135], 0, v[148:149]
	v_lshl_add_u64 v[236:237], v[132:133], 0, v[150:151]
	global_load_dwordx4 v[182:185], v[130:131], off
	v_lshl_add_u64 v[144:145], v[144:145], 0, v[148:149]
	v_lshl_add_u64 v[238:239], v[144:145], 0, v[150:151]
	v_mul_lo_u32 v253, v136, s86
	v_lshl_add_u32 v253, v137, 2, v253
	v_lshl_add_u64 v[254:255], v[146:147], 3, s[96:97]
	s_mov_b32 s100, 0x8000
	s_mov_b32 s101, 0
	s_movk_i32 s98, 0x100
	s_mov_b32 s99, 0
	s_mov_b32 s16, 4
	s_andn2_b64 vcc, exec, s[74:75]
	s_cbranch_vccnz .Lepi1_loop
	v_lshl_add_u64 v[132:133], s[4:5], 0, v[150:151]
	v_lshl_add_u64 v[134:135], s[8:9], 0, v[150:151]
	global_load_dwordx4 v[172:175], v[132:133], off offset:-4096
	global_load_dwordx4 v[176:179], v[134:135], off offset:-4096
.Lepi1_loop:
	global_load_dwordx4 v[130:133], v[236:237], off
	v_lshl_add_u64 v[236:237], v[236:237], 0, s[100:101]
	global_load_dwordx4 v[134:137], v[236:237], off
	v_lshl_add_u64 v[236:237], v[236:237], 0, s[100:101]
	global_load_dwordx4 v[138:141], v[236:237], off
	v_lshl_add_u64 v[236:237], v[236:237], 0, s[100:101]
	global_load_dwordx4 v[142:145], v[236:237], off
	v_lshl_add_u64 v[236:237], v[236:237], 0, s[100:101]
	s_andn2_b64 vcc, exec, s[74:75]
	s_cbranch_vccnz .Lepi1_nost
	global_load_dwordx2 v[146:147], v[254:255], off
	global_load_dwordx2 v[148:149], v[254:255], off offset:64
	global_load_dwordx2 v[150:151], v[254:255], off offset:128
	global_load_dwordx2 v[180:181], v[254:255], off offset:192
	v_lshl_add_u64 v[254:255], v[254:255], 0, s[98:99]
.Lepi1_nost:
	ds_read_b128 v[186:189], v253
	s_waitcnt vmcnt(3)
	s_andn2_b64 vcc, exec, s[74:75]
	s_cbranch_vccnz .Lepi1_noln_0
	v_pk_add_f32 v[130:131], v[130:131], v[146:147] op_sel_hi:[1,0] neg_lo:[0,1] neg_hi:[0,1]
	v_pk_add_f32 v[132:133], v[132:133], v[146:147] op_sel_hi:[1,0] neg_lo:[0,1] neg_hi:[0,1]
	v_pk_mul_f32 v[130:131], v[130:131], v[146:147] op_sel:[0,1]
	v_pk_mul_f32 v[132:133], v[132:133], v[146:147] op_sel:[0,1]
	v_pk_fma_f32 v[130:131], v[130:131], v[172:173], v[176:177]
	v_pk_fma_f32 v[132:133], v[132:133], v[174:175], v[178:179]
.Lepi1_noln_0:
	v_pk_mul_f32 v[130:131], v[130:131], s[56:57] op_sel_hi:[1,0]
	v_pk_mul_f32 v[132:133], v[132:133], s[56:57] op_sel_hi:[1,0]
	s_waitcnt lgkmcnt(0)
	v_pk_fma_f32 v[130:131], v[186:187], v[182:183], v[130:131]
	v_pk_fma_f32 v[132:133], v[188:189], v[184:185], v[132:133]
	global_store_dwordx4 v[238:239], v[130:133], off
	v_lshl_add_u64 v[238:239], v[238:239], 0, s[100:101]
	ds_read_b128 v[186:189], v253 offset:8448
	s_waitcnt vmcnt(3)
	s_andn2_b64 vcc, exec, s[74:75]
	s_cbranch_vccnz .Lepi1_noln_1
	v_pk_add_f32 v[134:135], v[134:135], v[148:149] op_sel_hi:[1,0] neg_lo:[0,1] neg_hi:[0,1]
	v_pk_add_f32 v[136:137], v[136:137], v[148:149] op_sel_hi:[1,0] neg_lo:[0,1] neg_hi:[0,1]
	v_pk_mul_f32 v[134:135], v[134:135], v[148:149] op_sel:[0,1]
	v_pk_mul_f32 v[136:137], v[136:137], v[148:149] op_sel:[0,1]
	v_pk_fma_f32 v[134:135], v[134:135], v[172:173], v[176:177]
	v_pk_fma_f32 v[136:137], v[136:137], v[174:175], v[178:179]
.Lepi1_noln_1:
	v_pk_mul_f32 v[134:135], v[134:135], s[56:57] op_sel_hi:[1,0]
	v_pk_mul_f32 v[136:137], v[136:137], s[56:57] op_sel_hi:[1,0]
	s_waitcnt lgkmcnt(0)
	v_pk_fma_f32 v[134:135], v[186:187], v[182:183], v[134:135]
	v_pk_fma_f32 v[136:137], v[188:189], v[184:185], v[136:137]
	global_store_dwordx4 v[238:239], v[134:137], off
	v_lshl_add_u64 v[238:239], v[238:239], 0, s[100:101]
	ds_read_b128 v[186:189], v253 offset:16896
	s_waitcnt vmcnt(3)
	s_andn2_b64 vcc, exec, s[74:75]
	s_cbranch_vccnz .Lepi1_noln_2
	v_pk_add_f32 v[138:139], v[138:139], v[150:151] op_sel_hi:[1,0] neg_lo:[0,1] neg_hi:[0,1]
	v_pk_add_f32 v[140:141], v[140:141], v[150:151] op_sel_hi:[1,0] neg_lo:[0,1] neg_hi:[0,1]
	v_pk_mul_f32 v[138:139], v[138:139], v[150:151] op_sel:[0,1]
	v_pk_mul_f32 v[140:141], v[140:141], v[150:151] op_sel:[0,1]
	v_pk_fma_f32 v[138:139], v[138:139], v[172:173], v[176:177]
	v_pk_fma_f32 v[140:141], v[140:141], v[174:175], v[178:179]
.Lepi1_noln_2:
	v_pk_mul_f32 v[138:139], v[138:139], s[56:57] op_sel_hi:[1,0]
	v_pk_mul_f32 v[140:141], v[140:141], s[56:57] op_sel_hi:[1,0]
	s_waitcnt lgkmcnt(0)
	v_pk_fma_f32 v[138:139], v[186:187], v[182:183], v[138:139]
	v_pk_fma_f32 v[140:141], v[188:189], v[184:185], v[140:141]
	global_store_dwordx4 v[238:239], v[138:141], off
	v_lshl_add_u64 v[238:239], v[238:239], 0, s[100:101]
	ds_read_b128 v[186:189], v253 offset:25344
	s_waitcnt vmcnt(3)
	s_andn2_b64 vcc, exec, s[74:75]
	s_cbranch_vccnz .Lepi1_noln_3
	v_pk_add_f32 v[142:143], v[142:143], v[180:181] op_sel_hi:[1,0] neg_lo:[0,1] neg_hi:[0,1]
	v_pk_add_f32 v[144:145], v[144:145], v[180:181] op_sel_hi:[1,0] neg_lo:[0,1] neg_hi:[0,1]
	v_pk_mul_f32 v[142:143], v[142:143], v[180:181] op_sel:[0,1]
	v_pk_mul_f32 v[144:145], v[144:145], v[180:181] op_sel:[0,1]
	v_pk_fma_f32 v[142:143], v[142:143], v[172:173], v[176:177]
	v_pk_fma_f32 v[144:145], v[144:145], v[174:175], v[178:179]
.Lepi1_noln_3:
	v_pk_mul_f32 v[142:143], v[142:143], s[56:57] op_sel_hi:[1,0]
	v_pk_mul_f32 v[144:145], v[144:145], s[56:57] op_sel_hi:[1,0]
	s_waitcnt lgkmcnt(0)
	v_pk_fma_f32 v[142:143], v[186:187], v[182:183], v[142:143]
	v_pk_fma_f32 v[144:145], v[188:189], v[184:185], v[144:145]
	global_store_dwordx4 v[238:239], v[142:145], off
	v_lshl_add_u64 v[238:239], v[238:239], 0, s[100:101]
	v_add_u32_e32 v253, 0x8400, v253
	s_sub_u32 s16, s16, 1
	s_cmp_lg_u32 s16, 0
	s_cbranch_scc1 .Lepi1_loop
	s_branch .LBB0_792
